# all four MFMA main loops: one static priority raise for the wave half that enters second instead of per-segment s_setprio toggles
# speedup vs baseline: 1.0085x; 1.0023x over previous
.LBB0_305:
	s_andn2_b64 vcc, exec, s[4:5]
	s_cbranch_vccnz .LBB0_568
	v_lshlrev_b32_e32 v128, 4, v156
	v_and_b32_e32 v0, 32, v156
	v_bfe_u32 v8, v156, 2, 4
	v_bitop3_b32 v6, v128, v0, 48 bitop3:0x6c
	v_and_b32_e32 v7, 64, v156
	v_lshrrev_b32_e32 v1, 3, v156
	s_movk_i32 s5, 0x70
	s_add_u32 s64, s40, 0x12634f00
	v_or_b32_e32 v0, v6, v7
	v_and_or_b32 v1, v1, s5, v8
	v_add_u32_e32 v9, 0x2000, v128
	s_addc_u32 s65, s41, 0
	v_lshl_or_b32 v130, v1, 12, v0
	v_lshrrev_b32_e32 v1, 7, v9
	s_movk_i32 s5, 0xf0
	s_ashr_i32 s7, s6, 31
	v_and_or_b32 v1, v1, s5, v8
	s_lshr_b32 s5, s12, 6
	s_lshl_b64 s[14:15], s[6:7], 20
	s_lshl_b32 s7, s52, 20
	s_lshr_b32 s4, s12, 8
	s_lshl_b32 s66, s5, 10
	s_and_b32 s7, s7, 0xff00000
	s_add_u32 s8, s40, s7
	v_writelane_b32 v243, s10, 0
	s_addc_u32 s9, s41, 0
	s_add_i32 s67, s66, 0
	v_mov_b32_e32 v135, 0
	v_writelane_b32 v243, s11, 1
	s_add_i32 m0, s67, 0x10000
	v_mov_b32_e32 v129, v135
	v_lshl_or_b32 v132, v1, 12, v0
	v_writelane_b32 v243, s12, 2
	v_lshl_add_u64 v[0:1], s[8:9], 0, v[128:129]
	global_load_lds_dwordx4 v128, s[8:9]
	s_mov_b64 s[12:13], 0x2000
	s_add_i32 m0, s67, 0x12000
	v_lshl_add_u64 v[2:3], v[0:1], 0, s[12:13]
	s_add_u32 s50, s64, s14
	global_load_lds_dwordx4 v[2:3], off
	s_addc_u32 s51, s65, s15
	s_mov_b32 m0, s67
	s_add_i32 s68, s67, 0x2000
	global_load_lds_dwordx4 v130, s[50:51]
	s_mov_b32 m0, s68
	s_mov_b64 s[14:15], 0x80000
	global_load_lds_dwordx4 v132, s[50:51]
	s_add_i32 m0, s67, 0x14000
	v_lshl_add_u64 v[2:3], v[0:1], 0, s[14:15]
	global_load_lds_dwordx4 v[2:3], off
	s_add_i32 m0, s67, 0x16000
	s_mov_b64 s[16:17], 0x82000
	s_add_u32 s18, s50, 0x80000
	v_lshl_add_u64 v[2:3], v[0:1], 0, s[16:17]
	s_addc_u32 s19, s51, 0
	s_add_i32 s69, s67, 0x4000
	global_load_lds_dwordx4 v[2:3], off
	s_mov_b32 m0, s69
	s_add_i32 s70, s67, 0x6000
	global_load_lds_dwordx4 v130, s[18:19]
	s_mov_b32 m0, s70
	v_mov_b32_e32 v131, v135
	global_load_lds_dwordx4 v132, s[18:19]
	s_load_dwordx2 s[18:19], s[0:1], 0x90
	v_mov_b32_e32 v133, v135
	v_lshrrev_b32_e32 v10, 2, v156
	s_mov_b32 s71, 0
	v_lshl_add_u64 v[4:5], s[50:51], 0, v[130:131]
	v_lshl_add_u64 v[2:3], s[50:51], 0, v[132:133]
	s_cmp_lg_u32 s4, 1
	s_movk_i32 s72, 0x4000
	s_cbranch_scc1 .LBB0_308
	s_barrier
	s_setprio 1

.LBB0_316:
	ds_read_b128 v[148:151], v163
	ds_read_b128 v[152:155], v163 offset:1024
	ds_read_b128 v[158:161], v163 offset:2048
	ds_read_b128 v[166:169], v163 offset:3072
	s_add_u32 s10, s8, 0xfff80080
	s_addc_u32 s11, s9, -1
	s_cmp_eq_u32 s57, 28
	s_cselect_b32 s51, s7, s11
	s_cselect_b32 s50, s45, s10
	s_cselect_b32 s59, s53, s56
	s_cselect_b32 s58, s54, s55
	v_lshl_add_u64 v[202:203], s[8:9], 0, v[138:139]
	s_add_i32 m0, s67, 0xc000
	ds_read_b128 v[170:173], v164
	ds_read_b128 v[174:177], v164 offset:1024
	ds_read_b128 v[178:181], v164 offset:2048
	ds_read_b128 v[182:185], v164 offset:3072
	ds_read_b128 v[186:189], v164 offset:4096
	ds_read_b128 v[190:193], v164 offset:5120
	ds_read_b128 v[194:197], v164 offset:6144
	ds_read_b128 v[198:201], v164 offset:7168
	global_load_lds_dwordx4 v[202:203], off
	v_lshl_add_u64 v[202:203], s[8:9], 0, v[140:141]
	s_add_i32 m0, s67, 0xe000
	s_nop 0
	global_load_lds_dwordx4 v[202:203], off
	s_waitcnt lgkmcnt(8)
	s_barrier
	s_waitcnt lgkmcnt(0)
	s_waitcnt lgkmcnt(0)
	v_mfma_f32_16x16x32_bf16 v[124:127], v[148:151], v[170:173], v[124:127]
	v_mfma_f32_16x16x32_bf16 v[120:123], v[158:161], v[170:173], v[120:123]
	v_mfma_f32_16x16x32_bf16 v[108:111], v[148:151], v[178:181], v[108:111]
	v_mfma_f32_16x16x32_bf16 v[104:107], v[158:161], v[178:181], v[104:107]
	v_mfma_f32_16x16x32_bf16 v[92:95], v[148:151], v[186:189], v[92:95]
	v_mfma_f32_16x16x32_bf16 v[88:91], v[158:161], v[186:189], v[88:91]
	v_mfma_f32_16x16x32_bf16 v[76:79], v[148:151], v[194:197], v[76:79]
	v_mfma_f32_16x16x32_bf16 v[72:75], v[158:161], v[194:197], v[72:75]
	v_mfma_f32_16x16x32_bf16 v[124:127], v[152:155], v[174:177], v[124:127]
	v_mfma_f32_16x16x32_bf16 v[120:123], v[166:169], v[174:177], v[120:123]
	v_mfma_f32_16x16x32_bf16 v[108:111], v[152:155], v[182:185], v[108:111]
	v_mfma_f32_16x16x32_bf16 v[104:107], v[166:169], v[182:185], v[104:107]
	v_mfma_f32_16x16x32_bf16 v[92:95], v[152:155], v[190:193], v[92:95]
	v_mfma_f32_16x16x32_bf16 v[88:91], v[166:169], v[190:193], v[88:91]
	v_mfma_f32_16x16x32_bf16 v[76:79], v[152:155], v[198:201], v[76:79]
	v_mfma_f32_16x16x32_bf16 v[72:75], v[166:169], v[198:201], v[72:75]
	s_barrier
	s_add_i32 s10, s82, s66
	v_lshl_add_u64 v[218:219], s[58:59], 0, v[128:129]
	s_mov_b32 m0, s10
	ds_read_b128 v[202:205], v165
	ds_read_b128 v[206:209], v165 offset:1024
	ds_read_b128 v[210:213], v165 offset:2048
	ds_read_b128 v[214:217], v165 offset:3072
	global_load_lds_dwordx4 v[218:219], off
	v_lshl_add_u64 v[220:221], v[218:219], 0, s[12:13]
	s_add_i32 m0, s10, 0x2000
	s_nop 0
	global_load_lds_dwordx4 v[220:221], off
	s_barrier
	s_waitcnt lgkmcnt(0)
	s_waitcnt lgkmcnt(0)
	v_mfma_f32_16x16x32_bf16 v[116:119], v[202:205], v[170:173], v[116:119]
	v_mfma_f32_16x16x32_bf16 v[112:115], v[210:213], v[170:173], v[112:115]
	v_mfma_f32_16x16x32_bf16 v[100:103], v[202:205], v[178:181], v[100:103]
	v_mfma_f32_16x16x32_bf16 v[96:99], v[210:213], v[178:181], v[96:99]
	v_mfma_f32_16x16x32_bf16 v[84:87], v[202:205], v[186:189], v[84:87]
	v_mfma_f32_16x16x32_bf16 v[80:83], v[210:213], v[186:189], v[80:83]
	v_mfma_f32_16x16x32_bf16 v[68:71], v[202:205], v[194:197], v[68:71]
	v_mfma_f32_16x16x32_bf16 v[64:67], v[210:213], v[194:197], v[64:67]
	v_mfma_f32_16x16x32_bf16 v[116:119], v[206:209], v[174:177], v[116:119]
	v_mfma_f32_16x16x32_bf16 v[112:115], v[214:217], v[174:177], v[112:115]
	v_mfma_f32_16x16x32_bf16 v[100:103], v[206:209], v[182:185], v[100:103]
	v_mfma_f32_16x16x32_bf16 v[96:99], v[214:217], v[182:185], v[96:99]
	v_mfma_f32_16x16x32_bf16 v[84:87], v[206:209], v[190:193], v[84:87]
	v_mfma_f32_16x16x32_bf16 v[80:83], v[214:217], v[190:193], v[80:83]
	v_mfma_f32_16x16x32_bf16 v[68:71], v[206:209], v[198:201], v[68:71]
	v_mfma_f32_16x16x32_bf16 v[64:67], v[214:217], v[198:201], v[64:67]
	s_mov_b32 m0, s67
	v_lshl_add_u64 v[220:221], s[50:51], 0, v[130:131]
	s_barrier
	ds_read_b128 v[170:173], v164 offset:16384
	ds_read_b128 v[174:177], v164 offset:17408
	ds_read_b128 v[178:181], v164 offset:18432
	ds_read_b128 v[182:185], v164 offset:19456
	ds_read_b128 v[186:189], v164 offset:20480
	ds_read_b128 v[190:193], v164 offset:21504
	ds_read_b128 v[194:197], v164 offset:22528
	ds_read_b128 v[198:201], v164 offset:23552
	global_load_lds_dwordx4 v[220:221], off
	v_lshl_add_u64 v[222:223], s[50:51], 0, v[132:133]
	s_mov_b32 m0, s68
	s_nop 0
	global_load_lds_dwordx4 v[222:223], off
	s_barrier
	s_waitcnt lgkmcnt(0)
	s_waitcnt lgkmcnt(0)
	v_mfma_f32_16x16x32_bf16 v[60:63], v[148:151], v[170:173], v[60:63]
	v_mfma_f32_16x16x32_bf16 v[56:59], v[158:161], v[170:173], v[56:59]
	v_mfma_f32_16x16x32_bf16 v[44:47], v[148:151], v[178:181], v[44:47]
	v_mfma_f32_16x16x32_bf16 v[40:43], v[158:161], v[178:181], v[40:43]
	v_mfma_f32_16x16x32_bf16 v[28:31], v[148:151], v[186:189], v[28:31]
	v_mfma_f32_16x16x32_bf16 v[24:27], v[158:161], v[186:189], v[24:27]
	v_mfma_f32_16x16x32_bf16 v[12:15], v[148:151], v[194:197], v[12:15]
	v_mfma_f32_16x16x32_bf16 v[8:11], v[158:161], v[194:197], v[8:11]
	v_mfma_f32_16x16x32_bf16 v[60:63], v[152:155], v[174:177], v[60:63]
	v_mfma_f32_16x16x32_bf16 v[56:59], v[166:169], v[174:177], v[56:59]
	v_mfma_f32_16x16x32_bf16 v[44:47], v[152:155], v[182:185], v[44:47]
	v_mfma_f32_16x16x32_bf16 v[40:43], v[166:169], v[182:185], v[40:43]
	v_mfma_f32_16x16x32_bf16 v[28:31], v[152:155], v[190:193], v[28:31]
	v_mfma_f32_16x16x32_bf16 v[24:27], v[166:169], v[190:193], v[24:27]
	v_mfma_f32_16x16x32_bf16 v[12:15], v[152:155], v[198:201], v[12:15]
	v_mfma_f32_16x16x32_bf16 v[8:11], v[166:169], v[198:201], v[8:11]
	s_barrier
	s_add_i32 s10, s83, s66
	v_lshl_add_u64 v[148:149], v[218:219], 0, s[14:15]
	s_mov_b32 m0, s10
	s_nop 0
	global_load_lds_dwordx4 v[148:149], off
	v_lshl_add_u64 v[148:149], v[218:219], 0, s[16:17]
	s_add_i32 m0, s10, 0x2000
	s_nop 0
	global_load_lds_dwordx4 v[148:149], off
	s_waitcnt vmcnt(6)
	s_barrier
	v_mfma_f32_16x16x32_bf16 v[52:55], v[202:205], v[170:173], v[52:55]
	v_mfma_f32_16x16x32_bf16 v[48:51], v[210:213], v[170:173], v[48:51]
	v_mfma_f32_16x16x32_bf16 v[36:39], v[202:205], v[178:181], v[36:39]
	v_mfma_f32_16x16x32_bf16 v[32:35], v[210:213], v[178:181], v[32:35]
	v_mfma_f32_16x16x32_bf16 v[20:23], v[202:205], v[186:189], v[20:23]
	v_mfma_f32_16x16x32_bf16 v[16:19], v[210:213], v[186:189], v[16:19]
	v_mfma_f32_16x16x32_bf16 v[4:7], v[202:205], v[194:197], v[4:7]
	v_mfma_f32_16x16x32_bf16 v[0:3], v[210:213], v[194:197], v[0:3]
	v_mfma_f32_16x16x32_bf16 v[52:55], v[206:209], v[174:177], v[52:55]
	v_mfma_f32_16x16x32_bf16 v[48:51], v[214:217], v[174:177], v[48:51]
	v_mfma_f32_16x16x32_bf16 v[36:39], v[206:209], v[182:185], v[36:39]
	v_mfma_f32_16x16x32_bf16 v[32:35], v[214:217], v[182:185], v[32:35]
	v_mfma_f32_16x16x32_bf16 v[20:23], v[206:209], v[190:193], v[20:23]
	v_mfma_f32_16x16x32_bf16 v[16:19], v[214:217], v[190:193], v[16:19]
	v_mfma_f32_16x16x32_bf16 v[4:7], v[206:209], v[198:201], v[4:7]
	v_mfma_f32_16x16x32_bf16 v[0:3], v[214:217], v[198:201], v[0:3]
	s_add_i32 s10, 0, 0x18000
	v_add_u32_e32 v134, s10, v157
	s_barrier
	ds_read_b128 v[148:151], v134
	ds_read_b128 v[152:155], v134 offset:1024
	ds_read_b128 v[158:161], v134 offset:2048
	ds_read_b128 v[166:169], v134 offset:3072
	s_add_u32 s50, s50, 0x80000
	s_addc_u32 s51, s51, 0
	s_mov_b32 m0, s69
	v_lshl_add_u64 v[202:203], s[50:51], 0, v[130:131]
	ds_read_b128 v[170:173], v164 offset:32768
	ds_read_b128 v[174:177], v164 offset:33792
	ds_read_b128 v[178:181], v164 offset:34816
	ds_read_b128 v[182:185], v164 offset:35840
	ds_read_b128 v[186:189], v164 offset:36864
	ds_read_b128 v[190:193], v164 offset:37888
	ds_read_b128 v[194:197], v164 offset:38912
	ds_read_b128 v[198:201], v164 offset:39936
	global_load_lds_dwordx4 v[202:203], off
	v_lshl_add_u64 v[202:203], s[50:51], 0, v[132:133]
	s_mov_b32 m0, s70
	s_nop 0
	global_load_lds_dwordx4 v[202:203], off
	s_waitcnt lgkmcnt(8)
	s_barrier
	s_waitcnt lgkmcnt(0)
	s_waitcnt lgkmcnt(0)
	v_mfma_f32_16x16x32_bf16 v[124:127], v[148:151], v[170:173], v[124:127]
	v_mfma_f32_16x16x32_bf16 v[120:123], v[158:161], v[170:173], v[120:123]
	v_mfma_f32_16x16x32_bf16 v[108:111], v[148:151], v[178:181], v[108:111]
	v_mfma_f32_16x16x32_bf16 v[104:107], v[158:161], v[178:181], v[104:107]
	v_mfma_f32_16x16x32_bf16 v[92:95], v[148:151], v[186:189], v[92:95]
	v_mfma_f32_16x16x32_bf16 v[88:91], v[158:161], v[186:189], v[88:91]
	v_mfma_f32_16x16x32_bf16 v[76:79], v[148:151], v[194:197], v[76:79]
	v_mfma_f32_16x16x32_bf16 v[72:75], v[158:161], v[194:197], v[72:75]
	v_mfma_f32_16x16x32_bf16 v[124:127], v[152:155], v[174:177], v[124:127]
	v_mfma_f32_16x16x32_bf16 v[120:123], v[166:169], v[174:177], v[120:123]
	v_mfma_f32_16x16x32_bf16 v[108:111], v[152:155], v[182:185], v[108:111]
	v_mfma_f32_16x16x32_bf16 v[104:107], v[166:169], v[182:185], v[104:107]
	v_mfma_f32_16x16x32_bf16 v[92:95], v[152:155], v[190:193], v[92:95]
	v_mfma_f32_16x16x32_bf16 v[88:91], v[166:169], v[190:193], v[88:91]
	v_mfma_f32_16x16x32_bf16 v[76:79], v[152:155], v[198:201], v[76:79]
	v_mfma_f32_16x16x32_bf16 v[72:75], v[166:169], v[198:201], v[72:75]
	s_barrier
	s_add_i32 s11, 0, 0x1c000
	s_add_i32 s10, s10, s66
	v_add_u32_e32 v134, s11, v157
	v_lshl_add_u64 v[224:225], v[218:219], 0, s[26:27]
	s_mov_b32 m0, s10
	ds_read_b128 v[202:205], v134
	ds_read_b128 v[206:209], v134 offset:1024
	ds_read_b128 v[210:213], v134 offset:2048
	ds_read_b128 v[214:217], v134 offset:3072
	global_load_lds_dwordx4 v[224:225], off
	v_lshl_add_u64 v[224:225], v[218:219], 0, s[28:29]
	s_add_i32 m0, s10, 0x2000
	s_nop 0
	global_load_lds_dwordx4 v[224:225], off
	s_barrier
	s_waitcnt lgkmcnt(0)
	s_waitcnt lgkmcnt(0)
	v_mfma_f32_16x16x32_bf16 v[116:119], v[202:205], v[170:173], v[116:119]
	v_mfma_f32_16x16x32_bf16 v[112:115], v[210:213], v[170:173], v[112:115]
	v_mfma_f32_16x16x32_bf16 v[100:103], v[202:205], v[178:181], v[100:103]
	v_mfma_f32_16x16x32_bf16 v[96:99], v[210:213], v[178:181], v[96:99]
	v_mfma_f32_16x16x32_bf16 v[84:87], v[202:205], v[186:189], v[84:87]
	v_mfma_f32_16x16x32_bf16 v[80:83], v[210:213], v[186:189], v[80:83]
	v_mfma_f32_16x16x32_bf16 v[68:71], v[202:205], v[194:197], v[68:71]
	v_mfma_f32_16x16x32_bf16 v[64:67], v[210:213], v[194:197], v[64:67]
	v_mfma_f32_16x16x32_bf16 v[116:119], v[206:209], v[174:177], v[116:119]
	v_mfma_f32_16x16x32_bf16 v[112:115], v[214:217], v[174:177], v[112:115]
	v_mfma_f32_16x16x32_bf16 v[100:103], v[206:209], v[182:185], v[100:103]
	v_mfma_f32_16x16x32_bf16 v[96:99], v[214:217], v[182:185], v[96:99]
	v_mfma_f32_16x16x32_bf16 v[84:87], v[206:209], v[190:193], v[84:87]
	v_mfma_f32_16x16x32_bf16 v[80:83], v[214:217], v[190:193], v[80:83]
	v_mfma_f32_16x16x32_bf16 v[68:71], v[206:209], v[198:201], v[68:71]
	v_mfma_f32_16x16x32_bf16 v[64:67], v[214:217], v[198:201], v[64:67]
	s_mov_b32 m0, s77
	v_lshl_add_u64 v[220:221], v[220:221], 0, s[30:31]
	s_barrier
	ds_read_b128 v[170:173], v164 offset:49152
	ds_read_b128 v[174:177], v164 offset:50176
	ds_read_b128 v[178:181], v164 offset:51200
	ds_read_b128 v[182:185], v164 offset:52224
	ds_read_b128 v[186:189], v164 offset:53248
	ds_read_b128 v[190:193], v164 offset:54272
	ds_read_b128 v[194:197], v164 offset:55296
	ds_read_b128 v[198:201], v164 offset:56320
	global_load_lds_dwordx4 v[220:221], off
	v_lshl_add_u64 v[220:221], v[222:223], 0, s[30:31]
	s_mov_b32 m0, s78
	s_nop 0
	global_load_lds_dwordx4 v[220:221], off
	s_barrier
	s_waitcnt lgkmcnt(0)
	s_waitcnt lgkmcnt(0)
	v_mfma_f32_16x16x32_bf16 v[60:63], v[148:151], v[170:173], v[60:63]
	v_mfma_f32_16x16x32_bf16 v[56:59], v[158:161], v[170:173], v[56:59]
	v_mfma_f32_16x16x32_bf16 v[44:47], v[148:151], v[178:181], v[44:47]
	v_mfma_f32_16x16x32_bf16 v[40:43], v[158:161], v[178:181], v[40:43]
	v_mfma_f32_16x16x32_bf16 v[28:31], v[148:151], v[186:189], v[28:31]
	v_mfma_f32_16x16x32_bf16 v[24:27], v[158:161], v[186:189], v[24:27]
	v_mfma_f32_16x16x32_bf16 v[12:15], v[148:151], v[194:197], v[12:15]
	v_mfma_f32_16x16x32_bf16 v[8:11], v[158:161], v[194:197], v[8:11]
	v_mfma_f32_16x16x32_bf16 v[60:63], v[152:155], v[174:177], v[60:63]
	v_mfma_f32_16x16x32_bf16 v[56:59], v[166:169], v[174:177], v[56:59]
	v_mfma_f32_16x16x32_bf16 v[44:47], v[152:155], v[182:185], v[44:47]
	v_mfma_f32_16x16x32_bf16 v[40:43], v[166:169], v[182:185], v[40:43]
	v_mfma_f32_16x16x32_bf16 v[28:31], v[152:155], v[190:193], v[28:31]
	v_mfma_f32_16x16x32_bf16 v[24:27], v[166:169], v[190:193], v[24:27]
	v_mfma_f32_16x16x32_bf16 v[12:15], v[152:155], v[198:201], v[12:15]
	v_mfma_f32_16x16x32_bf16 v[8:11], v[166:169], v[198:201], v[8:11]
	s_barrier
	s_add_i32 s10, s11, s66
	v_lshl_add_u64 v[148:149], v[218:219], 0, s[34:35]
	s_mov_b32 m0, s10
	s_nop 0
	global_load_lds_dwordx4 v[148:149], off
	v_lshl_add_u64 v[148:149], v[218:219], 0, s[38:39]
	s_add_i32 m0, s10, 0x2000
	s_nop 0
	global_load_lds_dwordx4 v[148:149], off
	s_waitcnt vmcnt(6)
	s_barrier
	v_mfma_f32_16x16x32_bf16 v[52:55], v[202:205], v[170:173], v[52:55]
	v_mfma_f32_16x16x32_bf16 v[48:51], v[210:213], v[170:173], v[48:51]
	v_mfma_f32_16x16x32_bf16 v[36:39], v[202:205], v[178:181], v[36:39]
	v_mfma_f32_16x16x32_bf16 v[32:35], v[210:213], v[178:181], v[32:35]
	v_mfma_f32_16x16x32_bf16 v[20:23], v[202:205], v[186:189], v[20:23]
	v_mfma_f32_16x16x32_bf16 v[16:19], v[210:213], v[186:189], v[16:19]
	v_mfma_f32_16x16x32_bf16 v[4:7], v[202:205], v[194:197], v[4:7]
	v_mfma_f32_16x16x32_bf16 v[0:3], v[210:213], v[194:197], v[0:3]
	v_mfma_f32_16x16x32_bf16 v[52:55], v[206:209], v[174:177], v[52:55]
	v_mfma_f32_16x16x32_bf16 v[48:51], v[214:217], v[174:177], v[48:51]
	v_mfma_f32_16x16x32_bf16 v[36:39], v[206:209], v[182:185], v[36:39]
	v_mfma_f32_16x16x32_bf16 v[32:35], v[214:217], v[182:185], v[32:35]
	v_mfma_f32_16x16x32_bf16 v[20:23], v[206:209], v[190:193], v[20:23]
	v_mfma_f32_16x16x32_bf16 v[16:19], v[214:217], v[190:193], v[16:19]
	v_mfma_f32_16x16x32_bf16 v[4:7], v[206:209], v[198:201], v[4:7]
	v_mfma_f32_16x16x32_bf16 v[0:3], v[214:217], v[198:201], v[0:3]
	s_add_i32 s57, s57, 2
	s_add_u32 s55, s55, 0x8000
	s_addc_u32 s56, s56, 0
	s_add_u32 s8, s8, 0x100
	s_addc_u32 s9, s9, 0
	s_cmp_gt_u32 s57, 29
	s_barrier
	s_cbranch_scc0 .LBB0_316
	s_lshl_b32 s95, s6, 8
	s_and_b32 s8, s52, 0xff
	s_add_i32 s95, s95, s79
	s_and_b32 s6, s52, 0xf8
	s_cmp_eq_u32 s6, 16
	s_cselect_b64 s[56:57], -1, 0
	v_and_b32_e32 v188, 4, v136
	v_mul_u32_u24_e32 v188, 6, v188
	v_mov_b32_e32 v189, 0
	s_mov_b32 s32, 1
	s_cmp_lg_u32 s6, 16
	s_cbranch_scc1 .Lproj_keep
	s_cmpk_ge_u32 s95, 0x4000
	s_cbranch_scc1 .Lproj_keep
	s_mov_b32 s32, 0

.LBB0_567:
	s_setprio 0
	v_readlane_b32 s10, v243, 0
	v_readlane_b32 s11, v243, 1
	s_barrier

.LBB0_1138:
	s_andn2_b64 vcc, exec, s[4:5]
	s_cbranch_vccnz .LBB0_1213
	v_lshlrev_b32_e32 v128, 4, v156
	s_waitcnt vmcnt(0)
	v_and_b32_e32 v0, 32, v156
	s_add_u32 s56, s40, 0x1900000
	v_bfe_u32 v8, v156, 2, 4
	v_bitop3_b32 v6, v128, v0, 48 bitop3:0x6c
	v_and_b32_e32 v7, 64, v156
	v_lshrrev_b32_e32 v1, 3, v156
	s_movk_i32 s5, 0x70
	s_addc_u32 s57, s41, 0
	v_or_b32_e32 v0, v6, v7
	v_and_or_b32 v1, v1, s5, v8
	v_add_u32_e32 v9, 0x2000, v128
	s_add_u32 s58, s40, 0x2d5d8f00
	v_lshl_or_b32 v130, v1, 12, v0
	v_lshrrev_b32_e32 v1, 7, v9
	s_movk_i32 s5, 0xf0
	s_addc_u32 s59, s41, 0
	v_and_or_b32 v1, v1, s5, v8
	s_lshr_b32 s5, s33, 6
	s_ashr_i32 s51, s50, 31
	s_lshl_b32 s8, s75, 20
	s_lshr_b32 s4, s33, 8
	s_lshl_b32 s60, s5, 10
	s_lshl_b64 s[6:7], s[50:51], 20
	s_and_b32 s8, s8, 0xff00000
	s_add_u32 s52, s56, s8
	s_addc_u32 s53, s57, 0
	s_add_i32 s61, s60, 0
	v_mov_b32_e32 v135, 0
	s_add_i32 m0, s61, 0x10000
	v_mov_b32_e32 v129, v135
	v_lshl_or_b32 v132, v1, 12, v0
	v_lshl_add_u64 v[0:1], s[52:53], 0, v[128:129]
	global_load_lds_dwordx4 v128, s[52:53]
	s_mov_b64 s[12:13], 0x2000
	s_add_i32 m0, s61, 0x12000
	v_lshl_add_u64 v[2:3], v[0:1], 0, s[12:13]
	s_add_u32 s54, s58, s6
	global_load_lds_dwordx4 v[2:3], off
	s_addc_u32 s55, s59, s7
	s_mov_b32 m0, s61
	s_add_i32 s62, s61, 0x2000
	global_load_lds_dwordx4 v130, s[54:55]
	s_mov_b32 m0, s62
	s_mov_b64 s[14:15], 0x80000
	global_load_lds_dwordx4 v132, s[54:55]
	s_add_i32 m0, s61, 0x14000
	v_lshl_add_u64 v[2:3], v[0:1], 0, s[14:15]
	global_load_lds_dwordx4 v[2:3], off
	s_add_i32 m0, s61, 0x16000
	s_mov_b64 s[18:19], 0x82000
	s_add_u32 s6, s54, 0x80000
	v_lshl_add_u64 v[2:3], v[0:1], 0, s[18:19]
	s_addc_u32 s7, s55, 0
	s_add_i32 s63, s61, 0x4000
	global_load_lds_dwordx4 v[2:3], off
	s_mov_b32 m0, s63
	s_add_i32 s64, s61, 0x6000
	global_load_lds_dwordx4 v130, s[6:7]
	s_mov_b32 m0, s64
	s_load_dwordx4 s[8:11], s[0:1], 0x0
	global_load_lds_dwordx4 v132, s[6:7]
	v_mov_b32_e32 v131, v135
	v_mov_b32_e32 v133, v135
	s_mov_b32 s65, 0
	v_lshl_add_u64 v[4:5], s[54:55], 0, v[130:131]
	s_cmp_lg_u32 s4, 1
	v_lshl_add_u64 v[2:3], s[54:55], 0, v[132:133]
	s_cbranch_scc1 .LBB0_1141
	s_barrier
	s_setprio 1

.LBB0_1153:
	ds_read_b128 v[146:149], v153
	ds_read_b128 v[158:161], v153 offset:1024
	ds_read_b128 v[162:165], v153 offset:2048
	ds_read_b128 v[166:169], v153 offset:3072
	s_add_u32 s54, s52, 0xfff80080
	s_addc_u32 s55, s53, -1
	s_cmp_eq_u32 s80, 28
	s_cselect_b32 s55, s45, s55
	s_cselect_b32 s54, s51, s54
	s_cselect_b32 s83, s76, s79
	s_cselect_b32 s82, s77, s78
	v_lshl_add_u64 v[202:203], s[52:53], 0, v[136:137]
	s_add_i32 m0, s61, 0xc000
	ds_read_b128 v[170:173], v154
	ds_read_b128 v[174:177], v154 offset:1024
	ds_read_b128 v[178:181], v154 offset:2048
	ds_read_b128 v[182:185], v154 offset:3072
	ds_read_b128 v[186:189], v154 offset:4096
	ds_read_b128 v[190:193], v154 offset:5120
	ds_read_b128 v[194:197], v154 offset:6144
	ds_read_b128 v[198:201], v154 offset:7168
	global_load_lds_dwordx4 v[202:203], off
	v_lshl_add_u64 v[202:203], s[52:53], 0, v[138:139]
	s_add_i32 m0, s61, 0xe000
	s_nop 0
	global_load_lds_dwordx4 v[202:203], off
	s_waitcnt lgkmcnt(8)
	s_barrier
	s_waitcnt lgkmcnt(0)
	s_waitcnt lgkmcnt(0)
	v_mfma_f32_16x16x32_bf16 v[124:127], v[146:149], v[170:173], v[124:127]
	v_mfma_f32_16x16x32_bf16 v[120:123], v[162:165], v[170:173], v[120:123]
	v_mfma_f32_16x16x32_bf16 v[108:111], v[146:149], v[178:181], v[108:111]
	v_mfma_f32_16x16x32_bf16 v[104:107], v[162:165], v[178:181], v[104:107]
	v_mfma_f32_16x16x32_bf16 v[92:95], v[146:149], v[186:189], v[92:95]
	v_mfma_f32_16x16x32_bf16 v[88:91], v[162:165], v[186:189], v[88:91]
	v_mfma_f32_16x16x32_bf16 v[76:79], v[146:149], v[194:197], v[76:79]
	v_mfma_f32_16x16x32_bf16 v[72:75], v[162:165], v[194:197], v[72:75]
	v_mfma_f32_16x16x32_bf16 v[124:127], v[158:161], v[174:177], v[124:127]
	v_mfma_f32_16x16x32_bf16 v[120:123], v[166:169], v[174:177], v[120:123]
	v_mfma_f32_16x16x32_bf16 v[108:111], v[158:161], v[182:185], v[108:111]
	v_mfma_f32_16x16x32_bf16 v[104:107], v[166:169], v[182:185], v[104:107]
	v_mfma_f32_16x16x32_bf16 v[92:95], v[158:161], v[190:193], v[92:95]
	v_mfma_f32_16x16x32_bf16 v[88:91], v[166:169], v[190:193], v[88:91]
	v_mfma_f32_16x16x32_bf16 v[76:79], v[158:161], v[198:201], v[76:79]
	v_mfma_f32_16x16x32_bf16 v[72:75], v[166:169], v[198:201], v[72:75]
	s_barrier
	s_add_i32 s81, s70, s60
	v_lshl_add_u64 v[218:219], s[82:83], 0, v[128:129]
	s_mov_b32 m0, s81
	ds_read_b128 v[202:205], v155
	ds_read_b128 v[206:209], v155 offset:1024
	ds_read_b128 v[210:213], v155 offset:2048
	ds_read_b128 v[214:217], v155 offset:3072
	global_load_lds_dwordx4 v[218:219], off
	v_lshl_add_u64 v[220:221], v[218:219], 0, s[12:13]
	s_add_i32 m0, s81, 0x2000
	s_nop 0
	global_load_lds_dwordx4 v[220:221], off
	s_barrier
	s_waitcnt lgkmcnt(0)
	s_waitcnt lgkmcnt(0)
	v_mfma_f32_16x16x32_bf16 v[116:119], v[202:205], v[170:173], v[116:119]
	v_mfma_f32_16x16x32_bf16 v[112:115], v[210:213], v[170:173], v[112:115]
	v_mfma_f32_16x16x32_bf16 v[100:103], v[202:205], v[178:181], v[100:103]
	v_mfma_f32_16x16x32_bf16 v[96:99], v[210:213], v[178:181], v[96:99]
	v_mfma_f32_16x16x32_bf16 v[84:87], v[202:205], v[186:189], v[84:87]
	v_mfma_f32_16x16x32_bf16 v[80:83], v[210:213], v[186:189], v[80:83]
	v_mfma_f32_16x16x32_bf16 v[68:71], v[202:205], v[194:197], v[68:71]
	v_mfma_f32_16x16x32_bf16 v[64:67], v[210:213], v[194:197], v[64:67]
	v_mfma_f32_16x16x32_bf16 v[116:119], v[206:209], v[174:177], v[116:119]
	v_mfma_f32_16x16x32_bf16 v[112:115], v[214:217], v[174:177], v[112:115]
	v_mfma_f32_16x16x32_bf16 v[100:103], v[206:209], v[182:185], v[100:103]
	v_mfma_f32_16x16x32_bf16 v[96:99], v[214:217], v[182:185], v[96:99]
	v_mfma_f32_16x16x32_bf16 v[84:87], v[206:209], v[190:193], v[84:87]
	v_mfma_f32_16x16x32_bf16 v[80:83], v[214:217], v[190:193], v[80:83]
	v_mfma_f32_16x16x32_bf16 v[68:71], v[206:209], v[198:201], v[68:71]
	v_mfma_f32_16x16x32_bf16 v[64:67], v[214:217], v[198:201], v[64:67]
	s_mov_b32 m0, s61
	v_lshl_add_u64 v[220:221], s[54:55], 0, v[130:131]
	s_barrier
	ds_read_b128 v[170:173], v154 offset:16384
	ds_read_b128 v[174:177], v154 offset:17408
	ds_read_b128 v[178:181], v154 offset:18432
	ds_read_b128 v[182:185], v154 offset:19456
	ds_read_b128 v[186:189], v154 offset:20480
	ds_read_b128 v[190:193], v154 offset:21504
	ds_read_b128 v[194:197], v154 offset:22528
	ds_read_b128 v[198:201], v154 offset:23552
	global_load_lds_dwordx4 v[220:221], off
	v_lshl_add_u64 v[222:223], s[54:55], 0, v[132:133]
	s_mov_b32 m0, s62
	s_nop 0
	global_load_lds_dwordx4 v[222:223], off
	s_barrier
	s_waitcnt lgkmcnt(0)
	s_waitcnt lgkmcnt(0)
	v_mfma_f32_16x16x32_bf16 v[60:63], v[146:149], v[170:173], v[60:63]
	v_mfma_f32_16x16x32_bf16 v[56:59], v[162:165], v[170:173], v[56:59]
	v_mfma_f32_16x16x32_bf16 v[44:47], v[146:149], v[178:181], v[44:47]
	v_mfma_f32_16x16x32_bf16 v[40:43], v[162:165], v[178:181], v[40:43]
	v_mfma_f32_16x16x32_bf16 v[28:31], v[146:149], v[186:189], v[28:31]
	v_mfma_f32_16x16x32_bf16 v[24:27], v[162:165], v[186:189], v[24:27]
	v_mfma_f32_16x16x32_bf16 v[12:15], v[146:149], v[194:197], v[12:15]
	v_mfma_f32_16x16x32_bf16 v[8:11], v[162:165], v[194:197], v[8:11]
	v_mfma_f32_16x16x32_bf16 v[60:63], v[158:161], v[174:177], v[60:63]
	v_mfma_f32_16x16x32_bf16 v[56:59], v[166:169], v[174:177], v[56:59]
	v_mfma_f32_16x16x32_bf16 v[44:47], v[158:161], v[182:185], v[44:47]
	v_mfma_f32_16x16x32_bf16 v[40:43], v[166:169], v[182:185], v[40:43]
	v_mfma_f32_16x16x32_bf16 v[28:31], v[158:161], v[190:193], v[28:31]
	v_mfma_f32_16x16x32_bf16 v[24:27], v[166:169], v[190:193], v[24:27]
	v_mfma_f32_16x16x32_bf16 v[12:15], v[158:161], v[198:201], v[12:15]
	v_mfma_f32_16x16x32_bf16 v[8:11], v[166:169], v[198:201], v[8:11]
	s_barrier
	s_add_i32 s81, s71, s60
	v_lshl_add_u64 v[146:147], v[218:219], 0, s[14:15]
	s_mov_b32 m0, s81
	s_nop 0
	global_load_lds_dwordx4 v[146:147], off
	v_lshl_add_u64 v[146:147], v[218:219], 0, s[18:19]
	s_add_i32 m0, s81, 0x2000
	s_nop 0
	global_load_lds_dwordx4 v[146:147], off
	s_waitcnt vmcnt(6)
	s_barrier
	v_mfma_f32_16x16x32_bf16 v[52:55], v[202:205], v[170:173], v[52:55]
	v_mfma_f32_16x16x32_bf16 v[48:51], v[210:213], v[170:173], v[48:51]
	v_mfma_f32_16x16x32_bf16 v[36:39], v[202:205], v[178:181], v[36:39]
	v_mfma_f32_16x16x32_bf16 v[32:35], v[210:213], v[178:181], v[32:35]
	v_mfma_f32_16x16x32_bf16 v[20:23], v[202:205], v[186:189], v[20:23]
	v_mfma_f32_16x16x32_bf16 v[16:19], v[210:213], v[186:189], v[16:19]
	v_mfma_f32_16x16x32_bf16 v[4:7], v[202:205], v[194:197], v[4:7]
	v_mfma_f32_16x16x32_bf16 v[0:3], v[210:213], v[194:197], v[0:3]
	v_mfma_f32_16x16x32_bf16 v[52:55], v[206:209], v[174:177], v[52:55]
	v_mfma_f32_16x16x32_bf16 v[48:51], v[214:217], v[174:177], v[48:51]
	v_mfma_f32_16x16x32_bf16 v[36:39], v[206:209], v[182:185], v[36:39]
	v_mfma_f32_16x16x32_bf16 v[32:35], v[214:217], v[182:185], v[32:35]
	v_mfma_f32_16x16x32_bf16 v[20:23], v[206:209], v[190:193], v[20:23]
	v_mfma_f32_16x16x32_bf16 v[16:19], v[214:217], v[190:193], v[16:19]
	v_mfma_f32_16x16x32_bf16 v[4:7], v[206:209], v[198:201], v[4:7]
	v_mfma_f32_16x16x32_bf16 v[0:3], v[214:217], v[198:201], v[0:3]
	s_add_i32 s81, 0, 0x18000
	v_add_u32_e32 v134, s81, v151
	s_barrier
	ds_read_b128 v[146:149], v134
	ds_read_b128 v[158:161], v134 offset:1024
	ds_read_b128 v[162:165], v134 offset:2048
	ds_read_b128 v[166:169], v134 offset:3072
	s_add_u32 s54, s54, 0x80000
	s_addc_u32 s55, s55, 0
	s_mov_b32 m0, s63
	v_lshl_add_u64 v[202:203], s[54:55], 0, v[130:131]
	ds_read_b128 v[170:173], v154 offset:32768
	ds_read_b128 v[174:177], v154 offset:33792
	ds_read_b128 v[178:181], v154 offset:34816
	ds_read_b128 v[182:185], v154 offset:35840
	ds_read_b128 v[186:189], v154 offset:36864
	ds_read_b128 v[190:193], v154 offset:37888
	ds_read_b128 v[194:197], v154 offset:38912
	ds_read_b128 v[198:201], v154 offset:39936
	global_load_lds_dwordx4 v[202:203], off
	v_lshl_add_u64 v[202:203], s[54:55], 0, v[132:133]
	s_mov_b32 m0, s64
	s_nop 0
	global_load_lds_dwordx4 v[202:203], off
	s_waitcnt lgkmcnt(8)
	s_barrier
	s_waitcnt lgkmcnt(0)
	s_waitcnt lgkmcnt(0)
	v_mfma_f32_16x16x32_bf16 v[124:127], v[146:149], v[170:173], v[124:127]
	v_mfma_f32_16x16x32_bf16 v[120:123], v[162:165], v[170:173], v[120:123]
	v_mfma_f32_16x16x32_bf16 v[108:111], v[146:149], v[178:181], v[108:111]
	v_mfma_f32_16x16x32_bf16 v[104:107], v[162:165], v[178:181], v[104:107]
	v_mfma_f32_16x16x32_bf16 v[92:95], v[146:149], v[186:189], v[92:95]
	v_mfma_f32_16x16x32_bf16 v[88:91], v[162:165], v[186:189], v[88:91]
	v_mfma_f32_16x16x32_bf16 v[76:79], v[146:149], v[194:197], v[76:79]
	v_mfma_f32_16x16x32_bf16 v[72:75], v[162:165], v[194:197], v[72:75]
	v_mfma_f32_16x16x32_bf16 v[124:127], v[158:161], v[174:177], v[124:127]
	v_mfma_f32_16x16x32_bf16 v[120:123], v[166:169], v[174:177], v[120:123]
	v_mfma_f32_16x16x32_bf16 v[108:111], v[158:161], v[182:185], v[108:111]
	v_mfma_f32_16x16x32_bf16 v[104:107], v[166:169], v[182:185], v[104:107]
	v_mfma_f32_16x16x32_bf16 v[92:95], v[158:161], v[190:193], v[92:95]
	v_mfma_f32_16x16x32_bf16 v[88:91], v[166:169], v[190:193], v[88:91]
	v_mfma_f32_16x16x32_bf16 v[76:79], v[158:161], v[198:201], v[76:79]
	v_mfma_f32_16x16x32_bf16 v[72:75], v[166:169], v[198:201], v[72:75]
	s_barrier
	s_add_i32 s54, 0, 0x1c000
	s_add_i32 s55, s81, s60
	v_add_u32_e32 v134, s54, v151
	v_lshl_add_u64 v[224:225], v[218:219], 0, s[26:27]
	s_mov_b32 m0, s55
	ds_read_b128 v[202:205], v134
	ds_read_b128 v[206:209], v134 offset:1024
	ds_read_b128 v[210:213], v134 offset:2048
	ds_read_b128 v[214:217], v134 offset:3072
	global_load_lds_dwordx4 v[224:225], off
	v_lshl_add_u64 v[224:225], v[218:219], 0, s[28:29]
	s_add_i32 m0, s55, 0x2000
	s_nop 0
	global_load_lds_dwordx4 v[224:225], off
	s_barrier
	s_waitcnt lgkmcnt(0)
	s_waitcnt lgkmcnt(0)
	v_mfma_f32_16x16x32_bf16 v[116:119], v[202:205], v[170:173], v[116:119]
	v_mfma_f32_16x16x32_bf16 v[112:115], v[210:213], v[170:173], v[112:115]
	v_mfma_f32_16x16x32_bf16 v[100:103], v[202:205], v[178:181], v[100:103]
	v_mfma_f32_16x16x32_bf16 v[96:99], v[210:213], v[178:181], v[96:99]
	v_mfma_f32_16x16x32_bf16 v[84:87], v[202:205], v[186:189], v[84:87]
	v_mfma_f32_16x16x32_bf16 v[80:83], v[210:213], v[186:189], v[80:83]
	v_mfma_f32_16x16x32_bf16 v[68:71], v[202:205], v[194:197], v[68:71]
	v_mfma_f32_16x16x32_bf16 v[64:67], v[210:213], v[194:197], v[64:67]
	v_mfma_f32_16x16x32_bf16 v[116:119], v[206:209], v[174:177], v[116:119]
	v_mfma_f32_16x16x32_bf16 v[112:115], v[214:217], v[174:177], v[112:115]
	v_mfma_f32_16x16x32_bf16 v[100:103], v[206:209], v[182:185], v[100:103]
	v_mfma_f32_16x16x32_bf16 v[96:99], v[214:217], v[182:185], v[96:99]
	v_mfma_f32_16x16x32_bf16 v[84:87], v[206:209], v[190:193], v[84:87]
	v_mfma_f32_16x16x32_bf16 v[80:83], v[214:217], v[190:193], v[80:83]
	v_mfma_f32_16x16x32_bf16 v[68:71], v[206:209], v[198:201], v[68:71]
	v_mfma_f32_16x16x32_bf16 v[64:67], v[214:217], v[198:201], v[64:67]
	s_mov_b32 m0, s66
	v_lshl_add_u64 v[220:221], v[220:221], 0, s[30:31]
	s_barrier
	ds_read_b128 v[170:173], v154 offset:49152
	ds_read_b128 v[174:177], v154 offset:50176
	ds_read_b128 v[178:181], v154 offset:51200
	ds_read_b128 v[182:185], v154 offset:52224
	ds_read_b128 v[186:189], v154 offset:53248
	ds_read_b128 v[190:193], v154 offset:54272
	ds_read_b128 v[194:197], v154 offset:55296
	ds_read_b128 v[198:201], v154 offset:56320
	global_load_lds_dwordx4 v[220:221], off
	v_lshl_add_u64 v[220:221], v[222:223], 0, s[30:31]
	s_mov_b32 m0, s67
	s_nop 0
	global_load_lds_dwordx4 v[220:221], off
	s_barrier
	s_waitcnt lgkmcnt(0)
	s_waitcnt lgkmcnt(0)
	v_mfma_f32_16x16x32_bf16 v[60:63], v[146:149], v[170:173], v[60:63]
	v_mfma_f32_16x16x32_bf16 v[56:59], v[162:165], v[170:173], v[56:59]
	v_mfma_f32_16x16x32_bf16 v[44:47], v[146:149], v[178:181], v[44:47]
	v_mfma_f32_16x16x32_bf16 v[40:43], v[162:165], v[178:181], v[40:43]
	v_mfma_f32_16x16x32_bf16 v[28:31], v[146:149], v[186:189], v[28:31]
	v_mfma_f32_16x16x32_bf16 v[24:27], v[162:165], v[186:189], v[24:27]
	v_mfma_f32_16x16x32_bf16 v[12:15], v[146:149], v[194:197], v[12:15]
	v_mfma_f32_16x16x32_bf16 v[8:11], v[162:165], v[194:197], v[8:11]
	v_mfma_f32_16x16x32_bf16 v[60:63], v[158:161], v[174:177], v[60:63]
	v_mfma_f32_16x16x32_bf16 v[56:59], v[166:169], v[174:177], v[56:59]
	v_mfma_f32_16x16x32_bf16 v[44:47], v[158:161], v[182:185], v[44:47]
	v_mfma_f32_16x16x32_bf16 v[40:43], v[166:169], v[182:185], v[40:43]
	v_mfma_f32_16x16x32_bf16 v[28:31], v[158:161], v[190:193], v[28:31]
	v_mfma_f32_16x16x32_bf16 v[24:27], v[166:169], v[190:193], v[24:27]
	v_mfma_f32_16x16x32_bf16 v[12:15], v[158:161], v[198:201], v[12:15]
	v_mfma_f32_16x16x32_bf16 v[8:11], v[166:169], v[198:201], v[8:11]
	s_barrier
	s_add_i32 s54, s54, s60
	v_lshl_add_u64 v[146:147], v[218:219], 0, s[34:35]
	s_mov_b32 m0, s54
	s_nop 0
	global_load_lds_dwordx4 v[146:147], off
	v_lshl_add_u64 v[146:147], v[218:219], 0, s[38:39]
	s_add_i32 m0, s54, 0x2000
	s_nop 0
	global_load_lds_dwordx4 v[146:147], off
	s_waitcnt vmcnt(6)
	s_barrier
	v_mfma_f32_16x16x32_bf16 v[52:55], v[202:205], v[170:173], v[52:55]
	v_mfma_f32_16x16x32_bf16 v[48:51], v[210:213], v[170:173], v[48:51]
	v_mfma_f32_16x16x32_bf16 v[36:39], v[202:205], v[178:181], v[36:39]
	v_mfma_f32_16x16x32_bf16 v[32:35], v[210:213], v[178:181], v[32:35]
	v_mfma_f32_16x16x32_bf16 v[20:23], v[202:205], v[186:189], v[20:23]
	v_mfma_f32_16x16x32_bf16 v[16:19], v[210:213], v[186:189], v[16:19]
	v_mfma_f32_16x16x32_bf16 v[4:7], v[202:205], v[194:197], v[4:7]
	v_mfma_f32_16x16x32_bf16 v[0:3], v[210:213], v[194:197], v[0:3]
	v_mfma_f32_16x16x32_bf16 v[52:55], v[206:209], v[174:177], v[52:55]
	v_mfma_f32_16x16x32_bf16 v[48:51], v[214:217], v[174:177], v[48:51]
	v_mfma_f32_16x16x32_bf16 v[36:39], v[206:209], v[182:185], v[36:39]
	v_mfma_f32_16x16x32_bf16 v[32:35], v[214:217], v[182:185], v[32:35]
	v_mfma_f32_16x16x32_bf16 v[20:23], v[206:209], v[190:193], v[20:23]
	v_mfma_f32_16x16x32_bf16 v[16:19], v[214:217], v[190:193], v[16:19]
	v_mfma_f32_16x16x32_bf16 v[4:7], v[206:209], v[198:201], v[4:7]
	v_mfma_f32_16x16x32_bf16 v[0:3], v[214:217], v[198:201], v[0:3]
	s_add_i32 s80, s80, 2
	s_add_u32 s78, s78, 0x8000
	s_addc_u32 s79, s79, 0
	s_add_u32 s52, s52, 0x100
	s_addc_u32 s53, s53, 0
	s_cmp_gt_u32 s80, 29
	s_barrier
	s_cbranch_scc0 .LBB0_1153
	s_lshl_b32 s45, s50, 21
	s_add_u32 s86, s20, s45
	s_addc_u32 s87, s21, 0
	s_add_u32 s84, s8, s45
	s_addc_u32 s85, s9, 0
	s_cmp_eq_u32 s50, 64
	s_cselect_b32 s84, s10, s84
	s_cselect_b32 s85, s11, s85
	s_lshl_b32 s45, s50, 20
	s_add_u32 s52, s22, s45
	s_addc_u32 s53, s23, 0
	v_and_b32_e32 v134, 8, v150
	v_and_b32_e32 v146, 0xfff7, v150
	v_lshl_add_u32 v147, v134, 1, v152
	s_lshl_b32 s45, s75, 8
	v_cmp_ne_u32_e32 vcc, 0, v134
	v_add_u32_e32 v147, s45, v147
	v_lshlrev_b32_e32 v146, 13, v146
	v_lshl_add_u32 v146, v147, 2, v146
	s_lshl_b32 s51, s50, 10
	s_cmp_eq_u32 s50, 64
	s_cselect_b32 s45, 1, 0
	s_add_u32 s50, s24, s51
	s_addc_u32 s51, s25, 0
	s_cmp_eq_u32 s45, 1
	s_cbranch_scc1 .Lepo_tail
	v_mov_b32_e32 v166, v146
	v_add_u32_e32 v167, 0x10000, v146
	global_load_dwordx4 v[170:173], v166, s[84:85]
	global_load_dwordx4 v[174:177], v167, s[84:85]
	global_load_dwordx4 v[178:181], v166, s[84:85] offset:512
	global_load_dwordx4 v[182:185], v167, s[84:85] offset:512
	v_add_u32_e32 v166, 0x20000, v146
	v_add_u32_e32 v167, 0x30000, v146
	global_load_dwordx4 v[186:189], v166, s[84:85]
	global_load_dwordx4 v[190:193], v167, s[84:85]
	global_load_dwordx4 v[194:197], v166, s[84:85] offset:512
	global_load_dwordx4 v[198:201], v167, s[84:85] offset:512
	v_add_u32_e32 v166, 0x40000, v146
	v_add_u32_e32 v167, 0x50000, v146
	global_load_dwordx4 v[202:205], v166, s[84:85]
	global_load_dwordx4 v[206:209], v167, s[84:85]
	global_load_dwordx4 v[210:213], v166, s[84:85] offset:512
	global_load_dwordx4 v[214:217], v167, s[84:85] offset:512
	v_mov_b32_e32 v158, v120
	v_mov_b32_e32 v159, v121
	v_mov_b32_e32 v160, v122
	v_mov_b32_e32 v161, v123
	v_mov_b32_e32 v162, v112
	v_mov_b32_e32 v163, v113
	v_mov_b32_e32 v164, v114
	v_mov_b32_e32 v165, v115
	v_mov_b32_dpp v120, v124 row_ror:8 row_mask:0xf bank_mask:0x3
	v_mov_b32_dpp v121, v125 row_ror:8 row_mask:0xf bank_mask:0x3
	v_mov_b32_dpp v122, v126 row_ror:8 row_mask:0xf bank_mask:0x3
	v_mov_b32_dpp v123, v127 row_ror:8 row_mask:0xf bank_mask:0x3
	v_mov_b32_dpp v112, v116 row_ror:8 row_mask:0xf bank_mask:0x3
	v_mov_b32_dpp v113, v117 row_ror:8 row_mask:0xf bank_mask:0x3
	v_mov_b32_dpp v114, v118 row_ror:8 row_mask:0xf bank_mask:0x3
	v_mov_b32_dpp v115, v119 row_ror:8 row_mask:0xf bank_mask:0x3
	v_mov_b32_dpp v124, v158 row_ror:8 row_mask:0xf bank_mask:0xc
	v_mov_b32_dpp v125, v159 row_ror:8 row_mask:0xf bank_mask:0xc
	v_mov_b32_dpp v126, v160 row_ror:8 row_mask:0xf bank_mask:0xc
	v_mov_b32_dpp v127, v161 row_ror:8 row_mask:0xf bank_mask:0xc
	v_mov_b32_dpp v116, v162 row_ror:8 row_mask:0xf bank_mask:0xc
	v_mov_b32_dpp v117, v163 row_ror:8 row_mask:0xf bank_mask:0xc
	v_mov_b32_dpp v118, v164 row_ror:8 row_mask:0xf bank_mask:0xc
	v_mov_b32_dpp v119, v165 row_ror:8 row_mask:0xf bank_mask:0xc
	v_mov_b32_e32 v166, v146
	v_add_u32_e32 v167, 0x10000, v146
	v_lshrrev_b32_e32 v168, 1, v166
	v_lshrrev_b32_e32 v169, 1, v167
	s_waitcnt vmcnt(8)
	v_pk_add_f32 v[124:125], v[124:125], v[170:171]
	v_pk_add_f32 v[126:127], v[126:127], v[172:173]
	v_pk_add_f32 v[120:121], v[120:121], v[174:175]
	v_pk_add_f32 v[122:123], v[122:123], v[176:177]
	v_pk_add_f32 v[116:117], v[116:117], v[178:179]
	v_pk_add_f32 v[118:119], v[118:119], v[180:181]
	v_pk_add_f32 v[112:113], v[112:113], v[182:183]
	v_pk_add_f32 v[114:115], v[114:115], v[184:185]
	global_store_dwordx4 v166, v[124:127], s[86:87]
	global_store_dwordx4 v167, v[120:123], s[86:87]
	global_store_dwordx4 v166, v[116:119], s[86:87] offset:512
	global_store_dwordx4 v167, v[112:115], s[86:87] offset:512
	v_cvt_pk_bf16_f32 v158, v124, v125
	v_cvt_pk_bf16_f32 v159, v126, v127
	v_cvt_pk_bf16_f32 v160, v120, v121
	v_cvt_pk_bf16_f32 v161, v122, v123
	v_cvt_pk_bf16_f32 v162, v116, v117
	v_cvt_pk_bf16_f32 v163, v118, v119
	v_cvt_pk_bf16_f32 v164, v112, v113
	v_cvt_pk_bf16_f32 v165, v114, v115
	global_store_dwordx2 v168, v[158:159], s[52:53]
	global_store_dwordx2 v169, v[160:161], s[52:53]
	global_store_dwordx2 v168, v[162:163], s[52:53] offset:256
	global_store_dwordx2 v169, v[164:165], s[52:53] offset:256
	v_mul_f32_e32 v148, v124, v124
	v_mul_f32_e32 v149, v120, v120
	v_fmac_f32_e32 v148, v125, v125
	v_fmac_f32_e32 v149, v121, v121
	v_fmac_f32_e32 v148, v126, v126
	v_fmac_f32_e32 v149, v122, v122
	v_fmac_f32_e32 v148, v127, v127
	v_fmac_f32_e32 v149, v123, v123
	v_fmac_f32_e32 v148, v116, v116
	v_fmac_f32_e32 v149, v112, v112
	v_fmac_f32_e32 v148, v117, v117
	v_fmac_f32_e32 v149, v113, v113
	v_fmac_f32_e32 v148, v118, v118
	v_fmac_f32_e32 v149, v114, v114
	v_fmac_f32_e32 v148, v119, v119
	v_fmac_f32_e32 v149, v115, v115
	s_nop 1
	v_add_f32_dpp v148, v148, v148 row_ror:8 row_mask:0xf bank_mask:0xf
	v_add_f32_dpp v149, v149, v149 row_ror:8 row_mask:0xf bank_mask:0xf
	v_mov_b32_e32 v134, v148
	v_mov_b32_e32 v147, v149
	s_nop 1
	v_permlane16_swap_b32_e32 v148, v134
	v_permlane16_swap_b32_e32 v149, v147
	v_add_f32_e32 v148, v148, v134
	v_add_f32_e32 v149, v149, v147
	v_mov_b32_e32 v134, v148
	v_mov_b32_e32 v147, v149
	s_nop 1
	v_permlane32_swap_b32_e32 v148, v134
	v_permlane32_swap_b32_e32 v149, v147
	v_add_f32_e32 v148, v148, v134
	v_add_f32_e32 v149, v149, v147
	v_cndmask_b32_e32 v148, v148, v149, vcc
	v_lshlrev_b32_e32 v134, 2, v150
	s_mov_b64 exec, s[4:5]
	global_atomic_add_f32 v134, v148, s[50:51]
	s_mov_b64 exec, -1
	v_add_u32_e32 v166, 0x60000, v146
	v_add_u32_e32 v167, 0x70000, v146
	global_load_dwordx4 v[170:173], v166, s[84:85]
	global_load_dwordx4 v[174:177], v167, s[84:85]
	global_load_dwordx4 v[178:181], v166, s[84:85] offset:512
	global_load_dwordx4 v[182:185], v167, s[84:85] offset:512
	v_mov_b32_e32 v158, v104
	v_mov_b32_e32 v159, v105
	v_mov_b32_e32 v160, v106
	v_mov_b32_e32 v161, v107
	v_mov_b32_e32 v162, v96
	v_mov_b32_e32 v163, v97
	v_mov_b32_e32 v164, v98
	v_mov_b32_e32 v165, v99
	v_mov_b32_dpp v104, v108 row_ror:8 row_mask:0xf bank_mask:0x3
	v_mov_b32_dpp v105, v109 row_ror:8 row_mask:0xf bank_mask:0x3
	v_mov_b32_dpp v106, v110 row_ror:8 row_mask:0xf bank_mask:0x3
	v_mov_b32_dpp v107, v111 row_ror:8 row_mask:0xf bank_mask:0x3
	v_mov_b32_dpp v96, v100 row_ror:8 row_mask:0xf bank_mask:0x3
	v_mov_b32_dpp v97, v101 row_ror:8 row_mask:0xf bank_mask:0x3
	v_mov_b32_dpp v98, v102 row_ror:8 row_mask:0xf bank_mask:0x3
	v_mov_b32_dpp v99, v103 row_ror:8 row_mask:0xf bank_mask:0x3
	v_mov_b32_dpp v108, v158 row_ror:8 row_mask:0xf bank_mask:0xc
	v_mov_b32_dpp v109, v159 row_ror:8 row_mask:0xf bank_mask:0xc
	v_mov_b32_dpp v110, v160 row_ror:8 row_mask:0xf bank_mask:0xc
	v_mov_b32_dpp v111, v161 row_ror:8 row_mask:0xf bank_mask:0xc
	v_mov_b32_dpp v100, v162 row_ror:8 row_mask:0xf bank_mask:0xc
	v_mov_b32_dpp v101, v163 row_ror:8 row_mask:0xf bank_mask:0xc
	v_mov_b32_dpp v102, v164 row_ror:8 row_mask:0xf bank_mask:0xc
	v_mov_b32_dpp v103, v165 row_ror:8 row_mask:0xf bank_mask:0xc
	v_add_u32_e32 v166, 0x20000, v146
	v_add_u32_e32 v167, 0x30000, v146
	v_lshrrev_b32_e32 v168, 1, v166
	v_lshrrev_b32_e32 v169, 1, v167
	s_waitcnt vmcnt(17)
	v_pk_add_f32 v[108:109], v[108:109], v[186:187]
	v_pk_add_f32 v[110:111], v[110:111], v[188:189]
	v_pk_add_f32 v[104:105], v[104:105], v[190:191]
	v_pk_add_f32 v[106:107], v[106:107], v[192:193]
	v_pk_add_f32 v[100:101], v[100:101], v[194:195]
	v_pk_add_f32 v[102:103], v[102:103], v[196:197]
	v_pk_add_f32 v[96:97], v[96:97], v[198:199]
	v_pk_add_f32 v[98:99], v[98:99], v[200:201]
	global_store_dwordx4 v166, v[108:111], s[86:87]
	global_store_dwordx4 v167, v[104:107], s[86:87]
	global_store_dwordx4 v166, v[100:103], s[86:87] offset:512
	global_store_dwordx4 v167, v[96:99], s[86:87] offset:512
	v_cvt_pk_bf16_f32 v158, v108, v109
	v_cvt_pk_bf16_f32 v159, v110, v111
	v_cvt_pk_bf16_f32 v160, v104, v105
	v_cvt_pk_bf16_f32 v161, v106, v107
	v_cvt_pk_bf16_f32 v162, v100, v101
	v_cvt_pk_bf16_f32 v163, v102, v103
	v_cvt_pk_bf16_f32 v164, v96, v97
	v_cvt_pk_bf16_f32 v165, v98, v99
	global_store_dwordx2 v168, v[158:159], s[52:53]
	global_store_dwordx2 v169, v[160:161], s[52:53]
	global_store_dwordx2 v168, v[162:163], s[52:53] offset:256
	global_store_dwordx2 v169, v[164:165], s[52:53] offset:256
	v_mul_f32_e32 v148, v108, v108
	v_mul_f32_e32 v149, v104, v104
	v_fmac_f32_e32 v148, v109, v109
	v_fmac_f32_e32 v149, v105, v105
	v_fmac_f32_e32 v148, v110, v110
	v_fmac_f32_e32 v149, v106, v106
	v_fmac_f32_e32 v148, v111, v111
	v_fmac_f32_e32 v149, v107, v107
	v_fmac_f32_e32 v148, v100, v100
	v_fmac_f32_e32 v149, v96, v96
	v_fmac_f32_e32 v148, v101, v101
	v_fmac_f32_e32 v149, v97, v97
	v_fmac_f32_e32 v148, v102, v102
	v_fmac_f32_e32 v149, v98, v98
	v_fmac_f32_e32 v148, v103, v103
	v_fmac_f32_e32 v149, v99, v99
	s_nop 1
	v_add_f32_dpp v148, v148, v148 row_ror:8 row_mask:0xf bank_mask:0xf
	v_add_f32_dpp v149, v149, v149 row_ror:8 row_mask:0xf bank_mask:0xf
	v_mov_b32_e32 v134, v148
	v_mov_b32_e32 v147, v149
	s_nop 1
	v_permlane16_swap_b32_e32 v148, v134
	v_permlane16_swap_b32_e32 v149, v147
	v_add_f32_e32 v148, v148, v134
	v_add_f32_e32 v149, v149, v147
	v_mov_b32_e32 v134, v148
	v_mov_b32_e32 v147, v149
	s_nop 1
	v_permlane32_swap_b32_e32 v148, v134
	v_permlane32_swap_b32_e32 v149, v147
	v_add_f32_e32 v148, v148, v134
	v_add_f32_e32 v149, v149, v147
	v_cndmask_b32_e32 v148, v148, v149, vcc
	v_lshlrev_b32_e32 v134, 2, v150
	s_mov_b64 exec, s[4:5]
	global_atomic_add_f32 v134, v148, s[50:51] offset:64
	s_mov_b64 exec, -1
	v_add_u32_e32 v166, 0x100000, v146
	v_add_u32_e32 v167, 0x110000, v146
	global_load_dwordx4 v[186:189], v166, s[84:85]
	global_load_dwordx4 v[190:193], v167, s[84:85]
	global_load_dwordx4 v[194:197], v166, s[84:85] offset:512
	global_load_dwordx4 v[198:201], v167, s[84:85] offset:512
	v_mov_b32_e32 v158, v88
	v_mov_b32_e32 v159, v89
	v_mov_b32_e32 v160, v90
	v_mov_b32_e32 v161, v91
	v_mov_b32_e32 v162, v80
	v_mov_b32_e32 v163, v81
	v_mov_b32_e32 v164, v82
	v_mov_b32_e32 v165, v83
	v_mov_b32_dpp v88, v92 row_ror:8 row_mask:0xf bank_mask:0x3
	v_mov_b32_dpp v89, v93 row_ror:8 row_mask:0xf bank_mask:0x3
	v_mov_b32_dpp v90, v94 row_ror:8 row_mask:0xf bank_mask:0x3
	v_mov_b32_dpp v91, v95 row_ror:8 row_mask:0xf bank_mask:0x3
	v_mov_b32_dpp v80, v84 row_ror:8 row_mask:0xf bank_mask:0x3
	v_mov_b32_dpp v81, v85 row_ror:8 row_mask:0xf bank_mask:0x3
	v_mov_b32_dpp v82, v86 row_ror:8 row_mask:0xf bank_mask:0x3
	v_mov_b32_dpp v83, v87 row_ror:8 row_mask:0xf bank_mask:0x3
	v_mov_b32_dpp v92, v158 row_ror:8 row_mask:0xf bank_mask:0xc
	v_mov_b32_dpp v93, v159 row_ror:8 row_mask:0xf bank_mask:0xc
	v_mov_b32_dpp v94, v160 row_ror:8 row_mask:0xf bank_mask:0xc
	v_mov_b32_dpp v95, v161 row_ror:8 row_mask:0xf bank_mask:0xc
	v_mov_b32_dpp v84, v162 row_ror:8 row_mask:0xf bank_mask:0xc
	v_mov_b32_dpp v85, v163 row_ror:8 row_mask:0xf bank_mask:0xc
	v_mov_b32_dpp v86, v164 row_ror:8 row_mask:0xf bank_mask:0xc
	v_mov_b32_dpp v87, v165 row_ror:8 row_mask:0xf bank_mask:0xc
	v_add_u32_e32 v166, 0x40000, v146
	v_add_u32_e32 v167, 0x50000, v146
	v_lshrrev_b32_e32 v168, 1, v166
	v_lshrrev_b32_e32 v169, 1, v167
	s_waitcnt vmcnt(26)
	v_pk_add_f32 v[92:93], v[92:93], v[202:203]
	v_pk_add_f32 v[94:95], v[94:95], v[204:205]
	v_pk_add_f32 v[88:89], v[88:89], v[206:207]
	v_pk_add_f32 v[90:91], v[90:91], v[208:209]
	v_pk_add_f32 v[84:85], v[84:85], v[210:211]
	v_pk_add_f32 v[86:87], v[86:87], v[212:213]
	v_pk_add_f32 v[80:81], v[80:81], v[214:215]
	v_pk_add_f32 v[82:83], v[82:83], v[216:217]
	global_store_dwordx4 v166, v[92:95], s[86:87]
	global_store_dwordx4 v167, v[88:91], s[86:87]
	global_store_dwordx4 v166, v[84:87], s[86:87] offset:512
	global_store_dwordx4 v167, v[80:83], s[86:87] offset:512
	v_cvt_pk_bf16_f32 v158, v92, v93
	v_cvt_pk_bf16_f32 v159, v94, v95
	v_cvt_pk_bf16_f32 v160, v88, v89
	v_cvt_pk_bf16_f32 v161, v90, v91
	v_cvt_pk_bf16_f32 v162, v84, v85
	v_cvt_pk_bf16_f32 v163, v86, v87
	v_cvt_pk_bf16_f32 v164, v80, v81
	v_cvt_pk_bf16_f32 v165, v82, v83
	global_store_dwordx2 v168, v[158:159], s[52:53]
	global_store_dwordx2 v169, v[160:161], s[52:53]
	global_store_dwordx2 v168, v[162:163], s[52:53] offset:256
	global_store_dwordx2 v169, v[164:165], s[52:53] offset:256
	v_mul_f32_e32 v148, v92, v92
	v_mul_f32_e32 v149, v88, v88
	v_fmac_f32_e32 v148, v93, v93
	v_fmac_f32_e32 v149, v89, v89
	v_fmac_f32_e32 v148, v94, v94
	v_fmac_f32_e32 v149, v90, v90
	v_fmac_f32_e32 v148, v95, v95
	v_fmac_f32_e32 v149, v91, v91
	v_fmac_f32_e32 v148, v84, v84
	v_fmac_f32_e32 v149, v80, v80
	v_fmac_f32_e32 v148, v85, v85
	v_fmac_f32_e32 v149, v81, v81
	v_fmac_f32_e32 v148, v86, v86
	v_fmac_f32_e32 v149, v82, v82
	v_fmac_f32_e32 v148, v87, v87
	v_fmac_f32_e32 v149, v83, v83
	s_nop 1
	v_add_f32_dpp v148, v148, v148 row_ror:8 row_mask:0xf bank_mask:0xf
	v_add_f32_dpp v149, v149, v149 row_ror:8 row_mask:0xf bank_mask:0xf
	v_mov_b32_e32 v134, v148
	v_mov_b32_e32 v147, v149
	s_nop 1
	v_permlane16_swap_b32_e32 v148, v134
	v_permlane16_swap_b32_e32 v149, v147
	v_add_f32_e32 v148, v148, v134
	v_add_f32_e32 v149, v149, v147
	v_mov_b32_e32 v134, v148
	v_mov_b32_e32 v147, v149
	s_nop 1
	v_permlane32_swap_b32_e32 v148, v134
	v_permlane32_swap_b32_e32 v149, v147
	v_add_f32_e32 v148, v148, v134
	v_add_f32_e32 v149, v149, v147
	v_cndmask_b32_e32 v148, v148, v149, vcc
	v_lshlrev_b32_e32 v134, 2, v150
	s_mov_b64 exec, s[4:5]
	global_atomic_add_f32 v134, v148, s[50:51] offset:128
	s_mov_b64 exec, -1
	v_add_u32_e32 v166, 0x120000, v146
	v_add_u32_e32 v167, 0x130000, v146
	global_load_dwordx4 v[202:205], v166, s[84:85]
	global_load_dwordx4 v[206:209], v167, s[84:85]
	global_load_dwordx4 v[210:213], v166, s[84:85] offset:512
	global_load_dwordx4 v[214:217], v167, s[84:85] offset:512
	v_mov_b32_e32 v158, v72
	v_mov_b32_e32 v159, v73
	v_mov_b32_e32 v160, v74
	v_mov_b32_e32 v161, v75
	v_mov_b32_e32 v162, v64
	v_mov_b32_e32 v163, v65
	v_mov_b32_e32 v164, v66
	v_mov_b32_e32 v165, v67
	v_mov_b32_dpp v72, v76 row_ror:8 row_mask:0xf bank_mask:0x3
	v_mov_b32_dpp v73, v77 row_ror:8 row_mask:0xf bank_mask:0x3
	v_mov_b32_dpp v74, v78 row_ror:8 row_mask:0xf bank_mask:0x3
	v_mov_b32_dpp v75, v79 row_ror:8 row_mask:0xf bank_mask:0x3
	v_mov_b32_dpp v64, v68 row_ror:8 row_mask:0xf bank_mask:0x3
	v_mov_b32_dpp v65, v69 row_ror:8 row_mask:0xf bank_mask:0x3
	v_mov_b32_dpp v66, v70 row_ror:8 row_mask:0xf bank_mask:0x3
	v_mov_b32_dpp v67, v71 row_ror:8 row_mask:0xf bank_mask:0x3
	v_mov_b32_dpp v76, v158 row_ror:8 row_mask:0xf bank_mask:0xc
	v_mov_b32_dpp v77, v159 row_ror:8 row_mask:0xf bank_mask:0xc
	v_mov_b32_dpp v78, v160 row_ror:8 row_mask:0xf bank_mask:0xc
	v_mov_b32_dpp v79, v161 row_ror:8 row_mask:0xf bank_mask:0xc
	v_mov_b32_dpp v68, v162 row_ror:8 row_mask:0xf bank_mask:0xc
	v_mov_b32_dpp v69, v163 row_ror:8 row_mask:0xf bank_mask:0xc
	v_mov_b32_dpp v70, v164 row_ror:8 row_mask:0xf bank_mask:0xc
	v_mov_b32_dpp v71, v165 row_ror:8 row_mask:0xf bank_mask:0xc
	v_add_u32_e32 v166, 0x60000, v146
	v_add_u32_e32 v167, 0x70000, v146
	v_lshrrev_b32_e32 v168, 1, v166
	v_lshrrev_b32_e32 v169, 1, v167
	s_waitcnt vmcnt(26)
	v_pk_add_f32 v[76:77], v[76:77], v[170:171]
	v_pk_add_f32 v[78:79], v[78:79], v[172:173]
	v_pk_add_f32 v[72:73], v[72:73], v[174:175]
	v_pk_add_f32 v[74:75], v[74:75], v[176:177]
	v_pk_add_f32 v[68:69], v[68:69], v[178:179]
	v_pk_add_f32 v[70:71], v[70:71], v[180:181]
	v_pk_add_f32 v[64:65], v[64:65], v[182:183]
	v_pk_add_f32 v[66:67], v[66:67], v[184:185]
	global_store_dwordx4 v166, v[76:79], s[86:87]
	global_store_dwordx4 v167, v[72:75], s[86:87]
	global_store_dwordx4 v166, v[68:71], s[86:87] offset:512
	global_store_dwordx4 v167, v[64:67], s[86:87] offset:512
	v_cvt_pk_bf16_f32 v158, v76, v77
	v_cvt_pk_bf16_f32 v159, v78, v79
	v_cvt_pk_bf16_f32 v160, v72, v73
	v_cvt_pk_bf16_f32 v161, v74, v75
	v_cvt_pk_bf16_f32 v162, v68, v69
	v_cvt_pk_bf16_f32 v163, v70, v71
	v_cvt_pk_bf16_f32 v164, v64, v65
	v_cvt_pk_bf16_f32 v165, v66, v67
	global_store_dwordx2 v168, v[158:159], s[52:53]
	global_store_dwordx2 v169, v[160:161], s[52:53]
	global_store_dwordx2 v168, v[162:163], s[52:53] offset:256
	global_store_dwordx2 v169, v[164:165], s[52:53] offset:256
	v_mul_f32_e32 v148, v76, v76
	v_mul_f32_e32 v149, v72, v72
	v_fmac_f32_e32 v148, v77, v77
	v_fmac_f32_e32 v149, v73, v73
	v_fmac_f32_e32 v148, v78, v78
	v_fmac_f32_e32 v149, v74, v74
	v_fmac_f32_e32 v148, v79, v79
	v_fmac_f32_e32 v149, v75, v75
	v_fmac_f32_e32 v148, v68, v68
	v_fmac_f32_e32 v149, v64, v64
	v_fmac_f32_e32 v148, v69, v69
	v_fmac_f32_e32 v149, v65, v65
	v_fmac_f32_e32 v148, v70, v70
	v_fmac_f32_e32 v149, v66, v66
	v_fmac_f32_e32 v148, v71, v71
	v_fmac_f32_e32 v149, v67, v67
	s_nop 1
	v_add_f32_dpp v148, v148, v148 row_ror:8 row_mask:0xf bank_mask:0xf
	v_add_f32_dpp v149, v149, v149 row_ror:8 row_mask:0xf bank_mask:0xf
	v_mov_b32_e32 v134, v148
	v_mov_b32_e32 v147, v149
	s_nop 1
	v_permlane16_swap_b32_e32 v148, v134
	v_permlane16_swap_b32_e32 v149, v147
	v_add_f32_e32 v148, v148, v134
	v_add_f32_e32 v149, v149, v147
	v_mov_b32_e32 v134, v148
	v_mov_b32_e32 v147, v149
	s_nop 1
	v_permlane32_swap_b32_e32 v148, v134
	v_permlane32_swap_b32_e32 v149, v147
	v_add_f32_e32 v148, v148, v134
	v_add_f32_e32 v149, v149, v147
	v_cndmask_b32_e32 v148, v148, v149, vcc
	v_lshlrev_b32_e32 v134, 2, v150
	s_mov_b64 exec, s[4:5]
	global_atomic_add_f32 v134, v148, s[50:51] offset:192
	s_mov_b64 exec, -1
	v_add_u32_e32 v166, 0x140000, v146
	v_add_u32_e32 v167, 0x150000, v146
	global_load_dwordx4 v[170:173], v166, s[84:85]
	global_load_dwordx4 v[174:177], v167, s[84:85]
	global_load_dwordx4 v[178:181], v166, s[84:85] offset:512
	global_load_dwordx4 v[182:185], v167, s[84:85] offset:512
	v_mov_b32_e32 v158, v56
	v_mov_b32_e32 v159, v57
	v_mov_b32_e32 v160, v58
	v_mov_b32_e32 v161, v59
	v_mov_b32_e32 v162, v48
	v_mov_b32_e32 v163, v49
	v_mov_b32_e32 v164, v50
	v_mov_b32_e32 v165, v51
	v_mov_b32_dpp v56, v60 row_ror:8 row_mask:0xf bank_mask:0x3
	v_mov_b32_dpp v57, v61 row_ror:8 row_mask:0xf bank_mask:0x3
	v_mov_b32_dpp v58, v62 row_ror:8 row_mask:0xf bank_mask:0x3
	v_mov_b32_dpp v59, v63 row_ror:8 row_mask:0xf bank_mask:0x3
	v_mov_b32_dpp v48, v52 row_ror:8 row_mask:0xf bank_mask:0x3
	v_mov_b32_dpp v49, v53 row_ror:8 row_mask:0xf bank_mask:0x3
	v_mov_b32_dpp v50, v54 row_ror:8 row_mask:0xf bank_mask:0x3
	v_mov_b32_dpp v51, v55 row_ror:8 row_mask:0xf bank_mask:0x3
	v_mov_b32_dpp v60, v158 row_ror:8 row_mask:0xf bank_mask:0xc
	v_mov_b32_dpp v61, v159 row_ror:8 row_mask:0xf bank_mask:0xc
	v_mov_b32_dpp v62, v160 row_ror:8 row_mask:0xf bank_mask:0xc
	v_mov_b32_dpp v63, v161 row_ror:8 row_mask:0xf bank_mask:0xc
	v_mov_b32_dpp v52, v162 row_ror:8 row_mask:0xf bank_mask:0xc
	v_mov_b32_dpp v53, v163 row_ror:8 row_mask:0xf bank_mask:0xc
	v_mov_b32_dpp v54, v164 row_ror:8 row_mask:0xf bank_mask:0xc
	v_mov_b32_dpp v55, v165 row_ror:8 row_mask:0xf bank_mask:0xc
	v_add_u32_e32 v166, 0x100000, v146
	v_add_u32_e32 v167, 0x110000, v146
	v_lshrrev_b32_e32 v168, 1, v166
	v_lshrrev_b32_e32 v169, 1, v167
	s_waitcnt vmcnt(26)
	v_pk_add_f32 v[60:61], v[60:61], v[186:187]
	v_pk_add_f32 v[62:63], v[62:63], v[188:189]
	v_pk_add_f32 v[56:57], v[56:57], v[190:191]
	v_pk_add_f32 v[58:59], v[58:59], v[192:193]
	v_pk_add_f32 v[52:53], v[52:53], v[194:195]
	v_pk_add_f32 v[54:55], v[54:55], v[196:197]
	v_pk_add_f32 v[48:49], v[48:49], v[198:199]
	v_pk_add_f32 v[50:51], v[50:51], v[200:201]
	global_store_dwordx4 v166, v[60:63], s[86:87]
	global_store_dwordx4 v167, v[56:59], s[86:87]
	global_store_dwordx4 v166, v[52:55], s[86:87] offset:512
	global_store_dwordx4 v167, v[48:51], s[86:87] offset:512
	v_cvt_pk_bf16_f32 v158, v60, v61
	v_cvt_pk_bf16_f32 v159, v62, v63
	v_cvt_pk_bf16_f32 v160, v56, v57
	v_cvt_pk_bf16_f32 v161, v58, v59
	v_cvt_pk_bf16_f32 v162, v52, v53
	v_cvt_pk_bf16_f32 v163, v54, v55
	v_cvt_pk_bf16_f32 v164, v48, v49
	v_cvt_pk_bf16_f32 v165, v50, v51
	global_store_dwordx2 v168, v[158:159], s[52:53]
	global_store_dwordx2 v169, v[160:161], s[52:53]
	global_store_dwordx2 v168, v[162:163], s[52:53] offset:256
	global_store_dwordx2 v169, v[164:165], s[52:53] offset:256
	v_mul_f32_e32 v148, v60, v60
	v_mul_f32_e32 v149, v56, v56
	v_fmac_f32_e32 v148, v61, v61
	v_fmac_f32_e32 v149, v57, v57
	v_fmac_f32_e32 v148, v62, v62
	v_fmac_f32_e32 v149, v58, v58
	v_fmac_f32_e32 v148, v63, v63
	v_fmac_f32_e32 v149, v59, v59
	v_fmac_f32_e32 v148, v52, v52
	v_fmac_f32_e32 v149, v48, v48
	v_fmac_f32_e32 v148, v53, v53
	v_fmac_f32_e32 v149, v49, v49
	v_fmac_f32_e32 v148, v54, v54
	v_fmac_f32_e32 v149, v50, v50
	v_fmac_f32_e32 v148, v55, v55
	v_fmac_f32_e32 v149, v51, v51
	s_nop 1
	v_add_f32_dpp v148, v148, v148 row_ror:8 row_mask:0xf bank_mask:0xf
	v_add_f32_dpp v149, v149, v149 row_ror:8 row_mask:0xf bank_mask:0xf
	v_mov_b32_e32 v134, v148
	v_mov_b32_e32 v147, v149
	s_nop 1
	v_permlane16_swap_b32_e32 v148, v134
	v_permlane16_swap_b32_e32 v149, v147
	v_add_f32_e32 v148, v148, v134
	v_add_f32_e32 v149, v149, v147
	v_mov_b32_e32 v134, v148
	v_mov_b32_e32 v147, v149
	s_nop 1
	v_permlane32_swap_b32_e32 v148, v134
	v_permlane32_swap_b32_e32 v149, v147
	v_add_f32_e32 v148, v148, v134
	v_add_f32_e32 v149, v149, v147
	v_cndmask_b32_e32 v148, v148, v149, vcc
	v_lshlrev_b32_e32 v134, 2, v150
	s_mov_b64 exec, s[4:5]
	global_atomic_add_f32 v134, v148, s[50:51] offset:512
	s_mov_b64 exec, -1
	v_add_u32_e32 v166, 0x160000, v146
	v_add_u32_e32 v167, 0x170000, v146
	global_load_dwordx4 v[186:189], v166, s[84:85]
	global_load_dwordx4 v[190:193], v167, s[84:85]
	global_load_dwordx4 v[194:197], v166, s[84:85] offset:512
	global_load_dwordx4 v[198:201], v167, s[84:85] offset:512
	v_mov_b32_e32 v158, v40
	v_mov_b32_e32 v159, v41
	v_mov_b32_e32 v160, v42
	v_mov_b32_e32 v161, v43
	v_mov_b32_e32 v162, v32
	v_mov_b32_e32 v163, v33
	v_mov_b32_e32 v164, v34
	v_mov_b32_e32 v165, v35
	v_mov_b32_dpp v40, v44 row_ror:8 row_mask:0xf bank_mask:0x3
	v_mov_b32_dpp v41, v45 row_ror:8 row_mask:0xf bank_mask:0x3
	v_mov_b32_dpp v42, v46 row_ror:8 row_mask:0xf bank_mask:0x3
	v_mov_b32_dpp v43, v47 row_ror:8 row_mask:0xf bank_mask:0x3
	v_mov_b32_dpp v32, v36 row_ror:8 row_mask:0xf bank_mask:0x3
	v_mov_b32_dpp v33, v37 row_ror:8 row_mask:0xf bank_mask:0x3
	v_mov_b32_dpp v34, v38 row_ror:8 row_mask:0xf bank_mask:0x3
	v_mov_b32_dpp v35, v39 row_ror:8 row_mask:0xf bank_mask:0x3
	v_mov_b32_dpp v44, v158 row_ror:8 row_mask:0xf bank_mask:0xc
	v_mov_b32_dpp v45, v159 row_ror:8 row_mask:0xf bank_mask:0xc
	v_mov_b32_dpp v46, v160 row_ror:8 row_mask:0xf bank_mask:0xc
	v_mov_b32_dpp v47, v161 row_ror:8 row_mask:0xf bank_mask:0xc
	v_mov_b32_dpp v36, v162 row_ror:8 row_mask:0xf bank_mask:0xc
	v_mov_b32_dpp v37, v163 row_ror:8 row_mask:0xf bank_mask:0xc
	v_mov_b32_dpp v38, v164 row_ror:8 row_mask:0xf bank_mask:0xc
	v_mov_b32_dpp v39, v165 row_ror:8 row_mask:0xf bank_mask:0xc
	v_add_u32_e32 v166, 0x120000, v146
	v_add_u32_e32 v167, 0x130000, v146
	v_lshrrev_b32_e32 v168, 1, v166
	v_lshrrev_b32_e32 v169, 1, v167
	s_waitcnt vmcnt(26)
	v_pk_add_f32 v[44:45], v[44:45], v[202:203]
	v_pk_add_f32 v[46:47], v[46:47], v[204:205]
	v_pk_add_f32 v[40:41], v[40:41], v[206:207]
	v_pk_add_f32 v[42:43], v[42:43], v[208:209]
	v_pk_add_f32 v[36:37], v[36:37], v[210:211]
	v_pk_add_f32 v[38:39], v[38:39], v[212:213]
	v_pk_add_f32 v[32:33], v[32:33], v[214:215]
	v_pk_add_f32 v[34:35], v[34:35], v[216:217]
	global_store_dwordx4 v166, v[44:47], s[86:87]
	global_store_dwordx4 v167, v[40:43], s[86:87]
	global_store_dwordx4 v166, v[36:39], s[86:87] offset:512
	global_store_dwordx4 v167, v[32:35], s[86:87] offset:512
	v_cvt_pk_bf16_f32 v158, v44, v45
	v_cvt_pk_bf16_f32 v159, v46, v47
	v_cvt_pk_bf16_f32 v160, v40, v41
	v_cvt_pk_bf16_f32 v161, v42, v43
	v_cvt_pk_bf16_f32 v162, v36, v37
	v_cvt_pk_bf16_f32 v163, v38, v39
	v_cvt_pk_bf16_f32 v164, v32, v33
	v_cvt_pk_bf16_f32 v165, v34, v35
	global_store_dwordx2 v168, v[158:159], s[52:53]
	global_store_dwordx2 v169, v[160:161], s[52:53]
	global_store_dwordx2 v168, v[162:163], s[52:53] offset:256
	global_store_dwordx2 v169, v[164:165], s[52:53] offset:256
	v_mul_f32_e32 v148, v44, v44
	v_mul_f32_e32 v149, v40, v40
	v_fmac_f32_e32 v148, v45, v45
	v_fmac_f32_e32 v149, v41, v41
	v_fmac_f32_e32 v148, v46, v46
	v_fmac_f32_e32 v149, v42, v42
	v_fmac_f32_e32 v148, v47, v47
	v_fmac_f32_e32 v149, v43, v43
	v_fmac_f32_e32 v148, v36, v36
	v_fmac_f32_e32 v149, v32, v32
	v_fmac_f32_e32 v148, v37, v37
	v_fmac_f32_e32 v149, v33, v33
	v_fmac_f32_e32 v148, v38, v38
	v_fmac_f32_e32 v149, v34, v34
	v_fmac_f32_e32 v148, v39, v39
	v_fmac_f32_e32 v149, v35, v35
	s_nop 1
	v_add_f32_dpp v148, v148, v148 row_ror:8 row_mask:0xf bank_mask:0xf
	v_add_f32_dpp v149, v149, v149 row_ror:8 row_mask:0xf bank_mask:0xf
	v_mov_b32_e32 v134, v148
	v_mov_b32_e32 v147, v149
	s_nop 1
	v_permlane16_swap_b32_e32 v148, v134
	v_permlane16_swap_b32_e32 v149, v147
	v_add_f32_e32 v148, v148, v134
	v_add_f32_e32 v149, v149, v147
	v_mov_b32_e32 v134, v148
	v_mov_b32_e32 v147, v149
	s_nop 1
	v_permlane32_swap_b32_e32 v148, v134
	v_permlane32_swap_b32_e32 v149, v147
	v_add_f32_e32 v148, v148, v134
	v_add_f32_e32 v149, v149, v147
	v_cndmask_b32_e32 v148, v148, v149, vcc
	v_lshlrev_b32_e32 v134, 2, v150
	s_mov_b64 exec, s[4:5]
	global_atomic_add_f32 v134, v148, s[50:51] offset:576
	s_mov_b64 exec, -1
	v_mov_b32_e32 v158, v24
	v_mov_b32_e32 v159, v25
	v_mov_b32_e32 v160, v26
	v_mov_b32_e32 v161, v27
	v_mov_b32_e32 v162, v16
	v_mov_b32_e32 v163, v17
	v_mov_b32_e32 v164, v18
	v_mov_b32_e32 v165, v19
	v_mov_b32_dpp v24, v28 row_ror:8 row_mask:0xf bank_mask:0x3
	v_mov_b32_dpp v25, v29 row_ror:8 row_mask:0xf bank_mask:0x3
	v_mov_b32_dpp v26, v30 row_ror:8 row_mask:0xf bank_mask:0x3
	v_mov_b32_dpp v27, v31 row_ror:8 row_mask:0xf bank_mask:0x3
	v_mov_b32_dpp v16, v20 row_ror:8 row_mask:0xf bank_mask:0x3
	v_mov_b32_dpp v17, v21 row_ror:8 row_mask:0xf bank_mask:0x3
	v_mov_b32_dpp v18, v22 row_ror:8 row_mask:0xf bank_mask:0x3
	v_mov_b32_dpp v19, v23 row_ror:8 row_mask:0xf bank_mask:0x3
	v_mov_b32_dpp v28, v158 row_ror:8 row_mask:0xf bank_mask:0xc
	v_mov_b32_dpp v29, v159 row_ror:8 row_mask:0xf bank_mask:0xc
	v_mov_b32_dpp v30, v160 row_ror:8 row_mask:0xf bank_mask:0xc
	v_mov_b32_dpp v31, v161 row_ror:8 row_mask:0xf bank_mask:0xc
	v_mov_b32_dpp v20, v162 row_ror:8 row_mask:0xf bank_mask:0xc
	v_mov_b32_dpp v21, v163 row_ror:8 row_mask:0xf bank_mask:0xc
	v_mov_b32_dpp v22, v164 row_ror:8 row_mask:0xf bank_mask:0xc
	v_mov_b32_dpp v23, v165 row_ror:8 row_mask:0xf bank_mask:0xc
	v_add_u32_e32 v166, 0x140000, v146
	v_add_u32_e32 v167, 0x150000, v146
	v_lshrrev_b32_e32 v168, 1, v166
	v_lshrrev_b32_e32 v169, 1, v167
	s_waitcnt vmcnt(22)
	v_pk_add_f32 v[28:29], v[28:29], v[170:171]
	v_pk_add_f32 v[30:31], v[30:31], v[172:173]
	v_pk_add_f32 v[24:25], v[24:25], v[174:175]
	v_pk_add_f32 v[26:27], v[26:27], v[176:177]
	v_pk_add_f32 v[20:21], v[20:21], v[178:179]
	v_pk_add_f32 v[22:23], v[22:23], v[180:181]
	v_pk_add_f32 v[16:17], v[16:17], v[182:183]
	v_pk_add_f32 v[18:19], v[18:19], v[184:185]
	global_store_dwordx4 v166, v[28:31], s[86:87]
	global_store_dwordx4 v167, v[24:27], s[86:87]
	global_store_dwordx4 v166, v[20:23], s[86:87] offset:512
	global_store_dwordx4 v167, v[16:19], s[86:87] offset:512
	v_cvt_pk_bf16_f32 v158, v28, v29
	v_cvt_pk_bf16_f32 v159, v30, v31
	v_cvt_pk_bf16_f32 v160, v24, v25
	v_cvt_pk_bf16_f32 v161, v26, v27
	v_cvt_pk_bf16_f32 v162, v20, v21
	v_cvt_pk_bf16_f32 v163, v22, v23
	v_cvt_pk_bf16_f32 v164, v16, v17
	v_cvt_pk_bf16_f32 v165, v18, v19
	global_store_dwordx2 v168, v[158:159], s[52:53]
	global_store_dwordx2 v169, v[160:161], s[52:53]
	global_store_dwordx2 v168, v[162:163], s[52:53] offset:256
	global_store_dwordx2 v169, v[164:165], s[52:53] offset:256
	v_mul_f32_e32 v148, v28, v28
	v_mul_f32_e32 v149, v24, v24
	v_fmac_f32_e32 v148, v29, v29
	v_fmac_f32_e32 v149, v25, v25
	v_fmac_f32_e32 v148, v30, v30
	v_fmac_f32_e32 v149, v26, v26
	v_fmac_f32_e32 v148, v31, v31
	v_fmac_f32_e32 v149, v27, v27
	v_fmac_f32_e32 v148, v20, v20
	v_fmac_f32_e32 v149, v16, v16
	v_fmac_f32_e32 v148, v21, v21
	v_fmac_f32_e32 v149, v17, v17
	v_fmac_f32_e32 v148, v22, v22
	v_fmac_f32_e32 v149, v18, v18
	v_fmac_f32_e32 v148, v23, v23
	v_fmac_f32_e32 v149, v19, v19
	s_nop 1
	v_add_f32_dpp v148, v148, v148 row_ror:8 row_mask:0xf bank_mask:0xf
	v_add_f32_dpp v149, v149, v149 row_ror:8 row_mask:0xf bank_mask:0xf
	v_mov_b32_e32 v134, v148
	v_mov_b32_e32 v147, v149
	s_nop 1
	v_permlane16_swap_b32_e32 v148, v134
	v_permlane16_swap_b32_e32 v149, v147
	v_add_f32_e32 v148, v148, v134
	v_add_f32_e32 v149, v149, v147
	v_mov_b32_e32 v134, v148
	v_mov_b32_e32 v147, v149
	s_nop 1
	v_permlane32_swap_b32_e32 v148, v134
	v_permlane32_swap_b32_e32 v149, v147
	v_add_f32_e32 v148, v148, v134
	v_add_f32_e32 v149, v149, v147
	v_cndmask_b32_e32 v148, v148, v149, vcc
	v_lshlrev_b32_e32 v134, 2, v150
	s_mov_b64 exec, s[4:5]
	global_atomic_add_f32 v134, v148, s[50:51] offset:640
	s_mov_b64 exec, -1
	v_mov_b32_e32 v158, v8
	v_mov_b32_e32 v159, v9
	v_mov_b32_e32 v160, v10
	v_mov_b32_e32 v161, v11
	v_mov_b32_e32 v162, v0
	v_mov_b32_e32 v163, v1
	v_mov_b32_e32 v164, v2
	v_mov_b32_e32 v165, v3
	v_mov_b32_dpp v8, v12 row_ror:8 row_mask:0xf bank_mask:0x3
	v_mov_b32_dpp v9, v13 row_ror:8 row_mask:0xf bank_mask:0x3
	v_mov_b32_dpp v10, v14 row_ror:8 row_mask:0xf bank_mask:0x3
	v_mov_b32_dpp v11, v15 row_ror:8 row_mask:0xf bank_mask:0x3
	v_mov_b32_dpp v0, v4 row_ror:8 row_mask:0xf bank_mask:0x3
	v_mov_b32_dpp v1, v5 row_ror:8 row_mask:0xf bank_mask:0x3
	v_mov_b32_dpp v2, v6 row_ror:8 row_mask:0xf bank_mask:0x3
	v_mov_b32_dpp v3, v7 row_ror:8 row_mask:0xf bank_mask:0x3
	v_mov_b32_dpp v12, v158 row_ror:8 row_mask:0xf bank_mask:0xc
	v_mov_b32_dpp v13, v159 row_ror:8 row_mask:0xf bank_mask:0xc
	v_mov_b32_dpp v14, v160 row_ror:8 row_mask:0xf bank_mask:0xc
	v_mov_b32_dpp v15, v161 row_ror:8 row_mask:0xf bank_mask:0xc
	v_mov_b32_dpp v4, v162 row_ror:8 row_mask:0xf bank_mask:0xc
	v_mov_b32_dpp v5, v163 row_ror:8 row_mask:0xf bank_mask:0xc
	v_mov_b32_dpp v6, v164 row_ror:8 row_mask:0xf bank_mask:0xc
	v_mov_b32_dpp v7, v165 row_ror:8 row_mask:0xf bank_mask:0xc
	v_add_u32_e32 v166, 0x160000, v146
	v_add_u32_e32 v167, 0x170000, v146
	v_lshrrev_b32_e32 v168, 1, v166
	v_lshrrev_b32_e32 v169, 1, v167
	s_waitcnt vmcnt(18)
	v_pk_add_f32 v[12:13], v[12:13], v[186:187]
	v_pk_add_f32 v[14:15], v[14:15], v[188:189]
	v_pk_add_f32 v[8:9], v[8:9], v[190:191]
	v_pk_add_f32 v[10:11], v[10:11], v[192:193]
	v_pk_add_f32 v[4:5], v[4:5], v[194:195]
	v_pk_add_f32 v[6:7], v[6:7], v[196:197]
	v_pk_add_f32 v[0:1], v[0:1], v[198:199]
	v_pk_add_f32 v[2:3], v[2:3], v[200:201]
	global_store_dwordx4 v166, v[12:15], s[86:87]
	global_store_dwordx4 v167, v[8:11], s[86:87]
	global_store_dwordx4 v166, v[4:7], s[86:87] offset:512
	global_store_dwordx4 v167, v[0:3], s[86:87] offset:512
	v_cvt_pk_bf16_f32 v158, v12, v13
	v_cvt_pk_bf16_f32 v159, v14, v15
	v_cvt_pk_bf16_f32 v160, v8, v9
	v_cvt_pk_bf16_f32 v161, v10, v11
	v_cvt_pk_bf16_f32 v162, v4, v5
	v_cvt_pk_bf16_f32 v163, v6, v7
	v_cvt_pk_bf16_f32 v164, v0, v1
	v_cvt_pk_bf16_f32 v165, v2, v3
	global_store_dwordx2 v168, v[158:159], s[52:53]
	global_store_dwordx2 v169, v[160:161], s[52:53]
	global_store_dwordx2 v168, v[162:163], s[52:53] offset:256
	global_store_dwordx2 v169, v[164:165], s[52:53] offset:256
	v_mul_f32_e32 v148, v12, v12
	v_mul_f32_e32 v149, v8, v8
	v_fmac_f32_e32 v148, v13, v13
	v_fmac_f32_e32 v149, v9, v9
	v_fmac_f32_e32 v148, v14, v14
	v_fmac_f32_e32 v149, v10, v10
	v_fmac_f32_e32 v148, v15, v15
	v_fmac_f32_e32 v149, v11, v11
	v_fmac_f32_e32 v148, v4, v4
	v_fmac_f32_e32 v149, v0, v0
	v_fmac_f32_e32 v148, v5, v5
	v_fmac_f32_e32 v149, v1, v1
	v_fmac_f32_e32 v148, v6, v6
	v_fmac_f32_e32 v149, v2, v2
	v_fmac_f32_e32 v148, v7, v7
	v_fmac_f32_e32 v149, v3, v3
	s_nop 1
	v_add_f32_dpp v148, v148, v148 row_ror:8 row_mask:0xf bank_mask:0xf
	v_add_f32_dpp v149, v149, v149 row_ror:8 row_mask:0xf bank_mask:0xf
	v_mov_b32_e32 v134, v148
	v_mov_b32_e32 v147, v149
	s_nop 1
	v_permlane16_swap_b32_e32 v148, v134
	v_permlane16_swap_b32_e32 v149, v147
	v_add_f32_e32 v148, v148, v134
	v_add_f32_e32 v149, v149, v147
	v_mov_b32_e32 v134, v148
	v_mov_b32_e32 v147, v149
	s_nop 1
	v_permlane32_swap_b32_e32 v148, v134
	v_permlane32_swap_b32_e32 v149, v147
	v_add_f32_e32 v148, v148, v134
	v_add_f32_e32 v149, v149, v147
	v_cndmask_b32_e32 v148, v148, v149, vcc
	v_lshlrev_b32_e32 v134, 2, v150
	s_mov_b64 exec, s[4:5]
	global_atomic_add_f32 v134, v148, s[50:51] offset:704
	s_mov_b64 exec, -1
	s_branch .LBB0_1142

.LBB0_1212:
	s_setprio 0
	s_barrier

.LBB0_1621:
	s_andn2_b64 vcc, exec, s[4:5]
	s_cbranch_vccnz .LBB0_1812
	s_add_u32 s33, s40, 0x28bb4f00
	s_addc_u32 s48, s41, 0
	s_add_u32 s49, s40, 0x4d00000
	v_lshlrev_b32_e32 v128, 4, v156
	s_waitcnt vmcnt(0)
	v_bfe_u32 v1, v156, 2, 4
	v_lshrrev_b32_e32 v2, 3, v156
	s_movk_i32 s5, 0x70
	s_addc_u32 s50, s41, 0
	v_and_or_b32 v2, v2, s5, v1
	v_add_u32_e32 v132, 0x2000, v128
	s_ashr_i32 s6, s68, 6
	v_mul_u32_u24_e32 v6, 0x2c00, v2
	v_lshrrev_b32_e32 v2, 7, v132
	s_movk_i32 s5, 0xf0
	s_and_b32 s6, s6, -4
	v_and_or_b32 v1, v2, s5, v1
	s_lshr_b32 s5, s3, 6
	s_ashr_i32 s7, s6, 31
	s_and_b32 s14, s68, 0xff
	s_lshr_b32 s4, s3, 8
	s_lshl_b32 s51, s5, 10
	s_lshl_b64 s[8:9], s[6:7], 7
	s_mul_i32 s14, s14, 0x2c0000
	s_add_u32 s14, s49, s14
	s_addc_u32 s15, s50, 0
	s_lshl_b64 s[6:7], s[6:7], 14
	s_add_u32 s38, s14, s6
	s_addc_u32 s39, s15, s7
	s_add_i32 s52, s51, 0
	s_add_i32 m0, s52, 0x10000
	s_mul_i32 s13, s69, 0x2c0000
	global_load_lds_dwordx4 v128, s[38:39]
	s_add_i32 m0, s52, 0x12000
	v_and_b32_e32 v0, 32, v156
	s_mul_hi_i32 s12, s69, 0x2c0000
	s_add_u32 s6, s33, s13
	v_bitop3_b32 v4, v128, v0, 48 bitop3:0x6c
	v_and_b32_e32 v5, 64, v156
	s_addc_u32 s7, s48, s12
	v_or_b32_e32 v0, v4, v5
	s_add_u32 s44, s6, s8
	v_or_b32_e32 v130, v6, v0
	v_mul_u32_u24_e32 v7, 0x2c00, v1
	global_load_lds_dwordx4 v132, s[38:39]
	s_addc_u32 s45, s7, s9
	s_mov_b32 m0, s52
	s_add_i32 s53, s52, 0x2000
	v_or_b32_e32 v134, v7, v0
	global_load_lds_dwordx4 v130, s[44:45]
	s_mov_b32 m0, s53
	s_add_u32 s6, s38, 0x160000
	global_load_lds_dwordx4 v134, s[44:45]
	s_addc_u32 s7, s39, 0
	s_add_i32 m0, s52, 0x14000
	v_mov_b32_e32 v133, 0
	global_load_lds_dwordx4 v128, s[6:7]
	s_add_i32 m0, s52, 0x16000
	v_mov_b32_e32 v131, v133
	global_load_lds_dwordx4 v132, s[6:7]
	s_add_u32 s6, s44, 0x160000
	s_addc_u32 s7, s45, 0
	s_add_i32 s54, s52, 0x4000
	s_mov_b32 m0, s54
	s_add_i32 s55, s52, 0x6000
	global_load_lds_dwordx4 v130, s[6:7]
	s_mov_b32 m0, s55
	v_mov_b32_e32 v135, v133
	global_load_lds_dwordx4 v134, s[6:7]
	s_load_dwordx2 s[12:13], s[0:1], 0x90
	s_load_dword s56, s[0:1], 0xa8
	v_lshrrev_b32_e32 v8, 2, v156
	s_mov_b32 s57, 0
	v_mov_b32_e32 v129, v133
	v_lshl_add_u64 v[2:3], s[44:45], 0, v[130:131]
	v_lshl_add_u64 v[0:1], s[44:45], 0, v[134:135]
	s_mov_b64 s[14:15], 0x160000
	s_cmp_lg_u32 s4, 1
	s_movk_i32 s58, 0x4000
	s_cbranch_scc1 .LBB0_1624
	s_barrier
	s_setprio 1

.LBB0_1640:
	ds_read_b128 v[146:149], v155
	ds_read_b128 v[160:163], v155 offset:1024
	ds_read_b128 v[164:167], v155 offset:2048
	ds_read_b128 v[168:171], v155 offset:3072
	s_add_i32 s73, s44, 2
	s_add_u32 s74, s38, 0xffea0080
	s_addc_u32 s45, s39, -1
	s_cmp_eq_u32 s70, s44
	s_cselect_b32 s44, s6, s74
	s_cselect_b32 s45, s7, s45
	s_cselect_b32 s75, s9, s72
	s_cselect_b32 s74, s8, s71
	v_lshl_add_u64 v[150:151], s[38:39], 0, v[136:137]
	s_add_i32 m0, s52, 0xc000
	ds_read_b128 v[172:175], v157
	ds_read_b128 v[176:179], v157 offset:1024
	ds_read_b128 v[180:183], v157 offset:2048
	ds_read_b128 v[184:187], v157 offset:3072
	ds_read_b128 v[188:191], v157 offset:4096
	ds_read_b128 v[192:195], v157 offset:5120
	ds_read_b128 v[196:199], v157 offset:6144
	ds_read_b128 v[200:203], v157 offset:7168
	global_load_lds_dwordx4 v[150:151], off
	v_lshl_add_u64 v[150:151], s[38:39], 0, v[138:139]
	s_add_i32 m0, s52, 0xe000
	s_nop 0
	global_load_lds_dwordx4 v[150:151], off
	s_waitcnt lgkmcnt(8)
	s_barrier
	s_waitcnt lgkmcnt(0)
	s_waitcnt lgkmcnt(0)
	v_mfma_f32_16x16x32_bf16 v[124:127], v[146:149], v[172:175], v[124:127]
	v_mfma_f32_16x16x32_bf16 v[120:123], v[164:167], v[172:175], v[120:123]
	v_mfma_f32_16x16x32_bf16 v[108:111], v[146:149], v[180:183], v[108:111]
	v_mfma_f32_16x16x32_bf16 v[104:107], v[164:167], v[180:183], v[104:107]
	v_mfma_f32_16x16x32_bf16 v[92:95], v[146:149], v[188:191], v[92:95]
	v_mfma_f32_16x16x32_bf16 v[88:91], v[164:167], v[188:191], v[88:91]
	v_mfma_f32_16x16x32_bf16 v[76:79], v[146:149], v[196:199], v[76:79]
	v_mfma_f32_16x16x32_bf16 v[72:75], v[164:167], v[196:199], v[72:75]
	v_mfma_f32_16x16x32_bf16 v[124:127], v[160:163], v[176:179], v[124:127]
	v_mfma_f32_16x16x32_bf16 v[120:123], v[168:171], v[176:179], v[120:123]
	v_mfma_f32_16x16x32_bf16 v[108:111], v[160:163], v[184:187], v[108:111]
	v_mfma_f32_16x16x32_bf16 v[104:107], v[168:171], v[184:187], v[104:107]
	v_mfma_f32_16x16x32_bf16 v[92:95], v[160:163], v[192:195], v[92:95]
	v_mfma_f32_16x16x32_bf16 v[88:91], v[168:171], v[192:195], v[88:91]
	v_mfma_f32_16x16x32_bf16 v[76:79], v[160:163], v[200:203], v[76:79]
	v_mfma_f32_16x16x32_bf16 v[72:75], v[168:171], v[200:203], v[72:75]
	s_barrier
	v_lshl_add_u64 v[150:151], s[74:75], 0, v[128:129]
	s_add_i32 s74, s63, s51
	s_mov_b32 m0, s74
	ds_read_b128 v[204:207], v158
	ds_read_b128 v[208:211], v158 offset:1024
	ds_read_b128 v[212:215], v158 offset:2048
	ds_read_b128 v[216:219], v158 offset:3072
	global_load_lds_dwordx4 v[150:151], off
	v_lshl_add_u64 v[220:221], v[150:151], 0, s[26:27]
	s_add_i32 m0, s74, 0x2000
	s_nop 0
	global_load_lds_dwordx4 v[220:221], off
	s_barrier
	s_waitcnt lgkmcnt(0)
	s_waitcnt lgkmcnt(0)
	v_mfma_f32_16x16x32_bf16 v[116:119], v[204:207], v[172:175], v[116:119]
	v_mfma_f32_16x16x32_bf16 v[112:115], v[212:215], v[172:175], v[112:115]
	v_mfma_f32_16x16x32_bf16 v[100:103], v[204:207], v[180:183], v[100:103]
	v_mfma_f32_16x16x32_bf16 v[96:99], v[212:215], v[180:183], v[96:99]
	v_mfma_f32_16x16x32_bf16 v[84:87], v[204:207], v[188:191], v[84:87]
	v_mfma_f32_16x16x32_bf16 v[80:83], v[212:215], v[188:191], v[80:83]
	v_mfma_f32_16x16x32_bf16 v[68:71], v[204:207], v[196:199], v[68:71]
	v_mfma_f32_16x16x32_bf16 v[64:67], v[212:215], v[196:199], v[64:67]
	v_mfma_f32_16x16x32_bf16 v[116:119], v[208:211], v[176:179], v[116:119]
	v_mfma_f32_16x16x32_bf16 v[112:115], v[216:219], v[176:179], v[112:115]
	v_mfma_f32_16x16x32_bf16 v[100:103], v[208:211], v[184:187], v[100:103]
	v_mfma_f32_16x16x32_bf16 v[96:99], v[216:219], v[184:187], v[96:99]
	v_mfma_f32_16x16x32_bf16 v[84:87], v[208:211], v[192:195], v[84:87]
	v_mfma_f32_16x16x32_bf16 v[80:83], v[216:219], v[192:195], v[80:83]
	v_mfma_f32_16x16x32_bf16 v[68:71], v[208:211], v[200:203], v[68:71]
	v_mfma_f32_16x16x32_bf16 v[64:67], v[216:219], v[200:203], v[64:67]
	s_mov_b32 m0, s52
	v_lshl_add_u64 v[220:221], s[44:45], 0, v[130:131]
	s_barrier
	ds_read_b128 v[172:175], v157 offset:16384
	ds_read_b128 v[176:179], v157 offset:17408
	ds_read_b128 v[180:183], v157 offset:18432
	ds_read_b128 v[184:187], v157 offset:19456
	ds_read_b128 v[188:191], v157 offset:20480
	ds_read_b128 v[192:195], v157 offset:21504
	ds_read_b128 v[196:199], v157 offset:22528
	ds_read_b128 v[200:203], v157 offset:23552
	global_load_lds_dwordx4 v[220:221], off
	v_lshl_add_u64 v[222:223], s[44:45], 0, v[134:135]
	s_mov_b32 m0, s53
	s_nop 0
	global_load_lds_dwordx4 v[222:223], off
	s_barrier
	s_waitcnt lgkmcnt(0)
	s_waitcnt lgkmcnt(0)
	v_mfma_f32_16x16x32_bf16 v[60:63], v[146:149], v[172:175], v[60:63]
	v_mfma_f32_16x16x32_bf16 v[56:59], v[164:167], v[172:175], v[56:59]
	v_mfma_f32_16x16x32_bf16 v[44:47], v[146:149], v[180:183], v[44:47]
	v_mfma_f32_16x16x32_bf16 v[40:43], v[164:167], v[180:183], v[40:43]
	v_mfma_f32_16x16x32_bf16 v[28:31], v[146:149], v[188:191], v[28:31]
	v_mfma_f32_16x16x32_bf16 v[24:27], v[164:167], v[188:191], v[24:27]
	v_mfma_f32_16x16x32_bf16 v[12:15], v[146:149], v[196:199], v[12:15]
	v_mfma_f32_16x16x32_bf16 v[8:11], v[164:167], v[196:199], v[8:11]
	v_mfma_f32_16x16x32_bf16 v[60:63], v[160:163], v[176:179], v[60:63]
	v_mfma_f32_16x16x32_bf16 v[56:59], v[168:171], v[176:179], v[56:59]
	v_mfma_f32_16x16x32_bf16 v[44:47], v[160:163], v[184:187], v[44:47]
	v_mfma_f32_16x16x32_bf16 v[40:43], v[168:171], v[184:187], v[40:43]
	v_mfma_f32_16x16x32_bf16 v[28:31], v[160:163], v[192:195], v[28:31]
	v_mfma_f32_16x16x32_bf16 v[24:27], v[168:171], v[192:195], v[24:27]
	v_mfma_f32_16x16x32_bf16 v[12:15], v[160:163], v[200:203], v[12:15]
	v_mfma_f32_16x16x32_bf16 v[8:11], v[168:171], v[200:203], v[8:11]
	s_barrier
	s_add_i32 s74, s64, s51
	v_lshl_add_u64 v[146:147], v[150:151], 0, s[14:15]
	s_mov_b32 m0, s74
	s_nop 0
	global_load_lds_dwordx4 v[146:147], off
	v_lshl_add_u64 v[146:147], v[150:151], 0, s[28:29]
	s_add_i32 m0, s74, 0x2000
	s_nop 0
	global_load_lds_dwordx4 v[146:147], off
	s_waitcnt vmcnt(6)
	s_barrier
	v_mfma_f32_16x16x32_bf16 v[52:55], v[204:207], v[172:175], v[52:55]
	v_mfma_f32_16x16x32_bf16 v[48:51], v[212:215], v[172:175], v[48:51]
	v_mfma_f32_16x16x32_bf16 v[36:39], v[204:207], v[180:183], v[36:39]
	v_mfma_f32_16x16x32_bf16 v[32:35], v[212:215], v[180:183], v[32:35]
	v_mfma_f32_16x16x32_bf16 v[20:23], v[204:207], v[188:191], v[20:23]
	v_mfma_f32_16x16x32_bf16 v[16:19], v[212:215], v[188:191], v[16:19]
	v_mfma_f32_16x16x32_bf16 v[4:7], v[204:207], v[196:199], v[4:7]
	v_mfma_f32_16x16x32_bf16 v[0:3], v[212:215], v[196:199], v[0:3]
	v_mfma_f32_16x16x32_bf16 v[52:55], v[208:211], v[176:179], v[52:55]
	v_mfma_f32_16x16x32_bf16 v[48:51], v[216:219], v[176:179], v[48:51]
	v_mfma_f32_16x16x32_bf16 v[36:39], v[208:211], v[184:187], v[36:39]
	v_mfma_f32_16x16x32_bf16 v[32:35], v[216:219], v[184:187], v[32:35]
	v_mfma_f32_16x16x32_bf16 v[20:23], v[208:211], v[192:195], v[20:23]
	v_mfma_f32_16x16x32_bf16 v[16:19], v[216:219], v[192:195], v[16:19]
	v_mfma_f32_16x16x32_bf16 v[4:7], v[208:211], v[200:203], v[4:7]
	v_mfma_f32_16x16x32_bf16 v[0:3], v[216:219], v[200:203], v[0:3]
	s_add_i32 s74, 0, 0x18000
	v_add_u32_e32 v132, s74, v153
	s_barrier
	ds_read_b128 v[146:149], v132
	ds_read_b128 v[160:163], v132 offset:1024
	ds_read_b128 v[164:167], v132 offset:2048
	ds_read_b128 v[168:171], v132 offset:3072
	s_add_u32 s44, s44, 0x160000
	s_addc_u32 s45, s45, 0
	s_mov_b32 m0, s54
	v_lshl_add_u64 v[204:205], s[44:45], 0, v[130:131]
	ds_read_b128 v[172:175], v157 offset:32768
	ds_read_b128 v[176:179], v157 offset:33792
	ds_read_b128 v[180:183], v157 offset:34816
	ds_read_b128 v[184:187], v157 offset:35840
	ds_read_b128 v[188:191], v157 offset:36864
	ds_read_b128 v[192:195], v157 offset:37888
	ds_read_b128 v[196:199], v157 offset:38912
	ds_read_b128 v[200:203], v157 offset:39936
	global_load_lds_dwordx4 v[204:205], off
	v_lshl_add_u64 v[204:205], s[44:45], 0, v[134:135]
	s_mov_b32 m0, s55
	s_nop 0
	global_load_lds_dwordx4 v[204:205], off
	s_waitcnt lgkmcnt(8)
	s_barrier
	s_waitcnt lgkmcnt(0)
	s_waitcnt lgkmcnt(0)
	v_mfma_f32_16x16x32_bf16 v[124:127], v[146:149], v[172:175], v[124:127]
	v_mfma_f32_16x16x32_bf16 v[120:123], v[164:167], v[172:175], v[120:123]
	v_mfma_f32_16x16x32_bf16 v[108:111], v[146:149], v[180:183], v[108:111]
	v_mfma_f32_16x16x32_bf16 v[104:107], v[164:167], v[180:183], v[104:107]
	v_mfma_f32_16x16x32_bf16 v[92:95], v[146:149], v[188:191], v[92:95]
	v_mfma_f32_16x16x32_bf16 v[88:91], v[164:167], v[188:191], v[88:91]
	v_mfma_f32_16x16x32_bf16 v[76:79], v[146:149], v[196:199], v[76:79]
	v_mfma_f32_16x16x32_bf16 v[72:75], v[164:167], v[196:199], v[72:75]
	v_mfma_f32_16x16x32_bf16 v[124:127], v[160:163], v[176:179], v[124:127]
	v_mfma_f32_16x16x32_bf16 v[120:123], v[168:171], v[176:179], v[120:123]
	v_mfma_f32_16x16x32_bf16 v[108:111], v[160:163], v[184:187], v[108:111]
	v_mfma_f32_16x16x32_bf16 v[104:107], v[168:171], v[184:187], v[104:107]
	v_mfma_f32_16x16x32_bf16 v[92:95], v[160:163], v[192:195], v[92:95]
	v_mfma_f32_16x16x32_bf16 v[88:91], v[168:171], v[192:195], v[88:91]
	v_mfma_f32_16x16x32_bf16 v[76:79], v[160:163], v[200:203], v[76:79]
	v_mfma_f32_16x16x32_bf16 v[72:75], v[168:171], v[200:203], v[72:75]
	s_barrier
	s_add_i32 s44, 0, 0x1c000
	s_add_i32 s45, s74, s51
	v_add_u32_e32 v132, s44, v153
	v_lshl_add_u64 v[224:225], v[150:151], 0, s[20:21]
	s_mov_b32 m0, s45
	ds_read_b128 v[204:207], v132
	ds_read_b128 v[208:211], v132 offset:1024
	ds_read_b128 v[212:215], v132 offset:2048
	ds_read_b128 v[216:219], v132 offset:3072
	global_load_lds_dwordx4 v[224:225], off
	v_lshl_add_u64 v[224:225], v[150:151], 0, s[30:31]
	s_add_i32 m0, s45, 0x2000
	s_nop 0
	global_load_lds_dwordx4 v[224:225], off
	s_barrier
	s_waitcnt lgkmcnt(0)
	s_waitcnt lgkmcnt(0)
	v_mfma_f32_16x16x32_bf16 v[116:119], v[204:207], v[172:175], v[116:119]
	v_mfma_f32_16x16x32_bf16 v[112:115], v[212:215], v[172:175], v[112:115]
	v_mfma_f32_16x16x32_bf16 v[100:103], v[204:207], v[180:183], v[100:103]
	v_mfma_f32_16x16x32_bf16 v[96:99], v[212:215], v[180:183], v[96:99]
	v_mfma_f32_16x16x32_bf16 v[84:87], v[204:207], v[188:191], v[84:87]
	v_mfma_f32_16x16x32_bf16 v[80:83], v[212:215], v[188:191], v[80:83]
	v_mfma_f32_16x16x32_bf16 v[68:71], v[204:207], v[196:199], v[68:71]
	v_mfma_f32_16x16x32_bf16 v[64:67], v[212:215], v[196:199], v[64:67]
	v_mfma_f32_16x16x32_bf16 v[116:119], v[208:211], v[176:179], v[116:119]
	v_mfma_f32_16x16x32_bf16 v[112:115], v[216:219], v[176:179], v[112:115]
	v_mfma_f32_16x16x32_bf16 v[100:103], v[208:211], v[184:187], v[100:103]
	v_mfma_f32_16x16x32_bf16 v[96:99], v[216:219], v[184:187], v[96:99]
	v_mfma_f32_16x16x32_bf16 v[84:87], v[208:211], v[192:195], v[84:87]
	v_mfma_f32_16x16x32_bf16 v[80:83], v[216:219], v[192:195], v[80:83]
	v_mfma_f32_16x16x32_bf16 v[68:71], v[208:211], v[200:203], v[68:71]
	v_mfma_f32_16x16x32_bf16 v[64:67], v[216:219], v[200:203], v[64:67]
	s_mov_b32 m0, s59
	v_lshl_add_u64 v[220:221], v[220:221], 0, s[18:19]
	s_barrier
	ds_read_b128 v[172:175], v157 offset:49152
	ds_read_b128 v[176:179], v157 offset:50176
	ds_read_b128 v[180:183], v157 offset:51200
	ds_read_b128 v[184:187], v157 offset:52224
	ds_read_b128 v[188:191], v157 offset:53248
	ds_read_b128 v[192:195], v157 offset:54272
	ds_read_b128 v[196:199], v157 offset:55296
	ds_read_b128 v[200:203], v157 offset:56320
	global_load_lds_dwordx4 v[220:221], off
	v_lshl_add_u64 v[220:221], v[222:223], 0, s[18:19]
	s_mov_b32 m0, s60
	s_nop 0
	global_load_lds_dwordx4 v[220:221], off
	s_barrier
	s_waitcnt lgkmcnt(0)
	s_waitcnt lgkmcnt(0)
	v_mfma_f32_16x16x32_bf16 v[60:63], v[146:149], v[172:175], v[60:63]
	v_mfma_f32_16x16x32_bf16 v[56:59], v[164:167], v[172:175], v[56:59]
	v_mfma_f32_16x16x32_bf16 v[44:47], v[146:149], v[180:183], v[44:47]
	v_mfma_f32_16x16x32_bf16 v[40:43], v[164:167], v[180:183], v[40:43]
	v_mfma_f32_16x16x32_bf16 v[28:31], v[146:149], v[188:191], v[28:31]
	v_mfma_f32_16x16x32_bf16 v[24:27], v[164:167], v[188:191], v[24:27]
	v_mfma_f32_16x16x32_bf16 v[12:15], v[146:149], v[196:199], v[12:15]
	v_mfma_f32_16x16x32_bf16 v[8:11], v[164:167], v[196:199], v[8:11]
	v_mfma_f32_16x16x32_bf16 v[60:63], v[160:163], v[176:179], v[60:63]
	v_mfma_f32_16x16x32_bf16 v[56:59], v[168:171], v[176:179], v[56:59]
	v_mfma_f32_16x16x32_bf16 v[44:47], v[160:163], v[184:187], v[44:47]
	v_mfma_f32_16x16x32_bf16 v[40:43], v[168:171], v[184:187], v[40:43]
	v_mfma_f32_16x16x32_bf16 v[28:31], v[160:163], v[192:195], v[28:31]
	v_mfma_f32_16x16x32_bf16 v[24:27], v[168:171], v[192:195], v[24:27]
	v_mfma_f32_16x16x32_bf16 v[12:15], v[160:163], v[200:203], v[12:15]
	v_mfma_f32_16x16x32_bf16 v[8:11], v[168:171], v[200:203], v[8:11]
	s_barrier
	s_add_i32 s44, s44, s51
	v_lshl_add_u64 v[146:147], v[150:151], 0, s[22:23]
	s_mov_b32 m0, s44
	s_nop 0
	global_load_lds_dwordx4 v[146:147], off
	v_lshl_add_u64 v[146:147], v[150:151], 0, s[34:35]
	s_add_i32 m0, s44, 0x2000
	s_nop 0
	global_load_lds_dwordx4 v[146:147], off
	s_waitcnt vmcnt(6)
	s_barrier
	v_mfma_f32_16x16x32_bf16 v[52:55], v[204:207], v[172:175], v[52:55]
	v_mfma_f32_16x16x32_bf16 v[48:51], v[212:215], v[172:175], v[48:51]
	v_mfma_f32_16x16x32_bf16 v[36:39], v[204:207], v[180:183], v[36:39]
	v_mfma_f32_16x16x32_bf16 v[32:35], v[212:215], v[180:183], v[32:35]
	v_mfma_f32_16x16x32_bf16 v[20:23], v[204:207], v[188:191], v[20:23]
	v_mfma_f32_16x16x32_bf16 v[16:19], v[212:215], v[188:191], v[16:19]
	v_mfma_f32_16x16x32_bf16 v[4:7], v[204:207], v[196:199], v[4:7]
	v_mfma_f32_16x16x32_bf16 v[0:3], v[212:215], v[196:199], v[0:3]
	v_mfma_f32_16x16x32_bf16 v[52:55], v[208:211], v[176:179], v[52:55]
	v_mfma_f32_16x16x32_bf16 v[48:51], v[216:219], v[176:179], v[48:51]
	v_mfma_f32_16x16x32_bf16 v[36:39], v[208:211], v[184:187], v[36:39]
	v_mfma_f32_16x16x32_bf16 v[32:35], v[216:219], v[184:187], v[32:35]
	v_mfma_f32_16x16x32_bf16 v[20:23], v[208:211], v[192:195], v[20:23]
	v_mfma_f32_16x16x32_bf16 v[16:19], v[216:219], v[192:195], v[16:19]
	v_mfma_f32_16x16x32_bf16 v[4:7], v[208:211], v[200:203], v[4:7]
	v_mfma_f32_16x16x32_bf16 v[0:3], v[216:219], v[200:203], v[0:3]
	s_add_u32 s71, s71, 0x8000
	s_addc_u32 s72, s72, 0
	s_add_u32 s38, s38, 0x100
	s_addc_u32 s39, s39, 0
	s_cmp_ge_u32 s73, s47
	s_mov_b32 s44, s73
	s_barrier
	s_cbranch_scc0 .LBB0_1640
	s_cmp_ge_u32 s69, 64
	s_cbranch_scc1 .Lepd_tail_hw
	s_lshl_b32 s80, s69, 21
	s_add_u32 s76, s16, s80
	s_addc_u32 s77, s17, 0
	s_add_u32 s78, s12, s80
	s_addc_u32 s79, s13, 0
	v_and_b32_e32 v132, 8, v152
	v_and_b32_e32 v146, 0xfff7, v152
	v_lshl_add_u32 v149, v132, 1, v154
	s_lshl_b32 s80, s68, 8
	s_and_b32 s80, s80, 0xff00
	v_add_u32_e32 v149, s80, v149
	v_lshlrev_b32_e32 v146, 13, v146
	v_lshl_add_u32 v146, v149, 2, v146
	v_mov_b32_e32 v147, v146
	v_add_u32_e32 v148, 0x10000, v146
	global_load_dwordx4 v[168:171], v147, s[76:77]
	global_load_dwordx4 v[172:175], v148, s[76:77]
	global_load_dwordx4 v[176:179], v147, s[76:77] offset:512
	global_load_dwordx4 v[180:183], v148, s[76:77] offset:512
	v_add_u32_e32 v147, 0x20000, v146
	v_add_u32_e32 v148, 0x30000, v146
	global_load_dwordx4 v[184:187], v147, s[76:77]
	global_load_dwordx4 v[188:191], v148, s[76:77]
	global_load_dwordx4 v[192:195], v147, s[76:77] offset:512
	global_load_dwordx4 v[196:199], v148, s[76:77] offset:512
	v_add_u32_e32 v147, 0x40000, v146
	v_add_u32_e32 v148, 0x50000, v146
	global_load_dwordx4 v[200:203], v147, s[76:77]
	global_load_dwordx4 v[204:207], v148, s[76:77]
	global_load_dwordx4 v[208:211], v147, s[76:77] offset:512
	global_load_dwordx4 v[212:215], v148, s[76:77] offset:512
	v_mov_b32_e32 v160, v120
	v_mov_b32_e32 v161, v121
	v_mov_b32_e32 v162, v122
	v_mov_b32_e32 v163, v123
	v_mov_b32_e32 v164, v112
	v_mov_b32_e32 v165, v113
	v_mov_b32_e32 v166, v114
	v_mov_b32_e32 v167, v115
	v_mov_b32_dpp v120, v124 row_ror:8 row_mask:0xf bank_mask:0x3
	v_mov_b32_dpp v121, v125 row_ror:8 row_mask:0xf bank_mask:0x3
	v_mov_b32_dpp v122, v126 row_ror:8 row_mask:0xf bank_mask:0x3
	v_mov_b32_dpp v123, v127 row_ror:8 row_mask:0xf bank_mask:0x3
	v_mov_b32_dpp v112, v116 row_ror:8 row_mask:0xf bank_mask:0x3
	v_mov_b32_dpp v113, v117 row_ror:8 row_mask:0xf bank_mask:0x3
	v_mov_b32_dpp v114, v118 row_ror:8 row_mask:0xf bank_mask:0x3
	v_mov_b32_dpp v115, v119 row_ror:8 row_mask:0xf bank_mask:0x3
	v_mov_b32_dpp v124, v160 row_ror:8 row_mask:0xf bank_mask:0xc
	v_mov_b32_dpp v125, v161 row_ror:8 row_mask:0xf bank_mask:0xc
	v_mov_b32_dpp v126, v162 row_ror:8 row_mask:0xf bank_mask:0xc
	v_mov_b32_dpp v127, v163 row_ror:8 row_mask:0xf bank_mask:0xc
	v_mov_b32_dpp v116, v164 row_ror:8 row_mask:0xf bank_mask:0xc
	v_mov_b32_dpp v117, v165 row_ror:8 row_mask:0xf bank_mask:0xc
	v_mov_b32_dpp v118, v166 row_ror:8 row_mask:0xf bank_mask:0xc
	v_mov_b32_dpp v119, v167 row_ror:8 row_mask:0xf bank_mask:0xc
	v_mov_b32_e32 v147, v146
	v_add_u32_e32 v148, 0x10000, v146
	s_waitcnt vmcnt(8)
	v_pk_add_f32 v[124:125], v[124:125], v[168:169]
	v_pk_add_f32 v[126:127], v[126:127], v[170:171]
	v_pk_add_f32 v[120:121], v[120:121], v[172:173]
	v_pk_add_f32 v[122:123], v[122:123], v[174:175]
	v_pk_add_f32 v[116:117], v[116:117], v[176:177]
	v_pk_add_f32 v[118:119], v[118:119], v[178:179]
	v_pk_add_f32 v[112:113], v[112:113], v[180:181]
	v_pk_add_f32 v[114:115], v[114:115], v[182:183]
	global_store_dwordx4 v147, v[124:127], s[78:79]
	global_store_dwordx4 v148, v[120:123], s[78:79]
	global_store_dwordx4 v147, v[116:119], s[78:79] offset:512
	global_store_dwordx4 v148, v[112:115], s[78:79] offset:512
	v_add_u32_e32 v147, 0x60000, v146
	v_add_u32_e32 v148, 0x70000, v146
	global_load_dwordx4 v[168:171], v147, s[76:77]
	global_load_dwordx4 v[172:175], v148, s[76:77]
	global_load_dwordx4 v[176:179], v147, s[76:77] offset:512
	global_load_dwordx4 v[180:183], v148, s[76:77] offset:512
	v_mov_b32_e32 v160, v104
	v_mov_b32_e32 v161, v105
	v_mov_b32_e32 v162, v106
	v_mov_b32_e32 v163, v107
	v_mov_b32_e32 v164, v96
	v_mov_b32_e32 v165, v97
	v_mov_b32_e32 v166, v98
	v_mov_b32_e32 v167, v99
	v_mov_b32_dpp v104, v108 row_ror:8 row_mask:0xf bank_mask:0x3
	v_mov_b32_dpp v105, v109 row_ror:8 row_mask:0xf bank_mask:0x3
	v_mov_b32_dpp v106, v110 row_ror:8 row_mask:0xf bank_mask:0x3
	v_mov_b32_dpp v107, v111 row_ror:8 row_mask:0xf bank_mask:0x3
	v_mov_b32_dpp v96, v100 row_ror:8 row_mask:0xf bank_mask:0x3
	v_mov_b32_dpp v97, v101 row_ror:8 row_mask:0xf bank_mask:0x3
	v_mov_b32_dpp v98, v102 row_ror:8 row_mask:0xf bank_mask:0x3
	v_mov_b32_dpp v99, v103 row_ror:8 row_mask:0xf bank_mask:0x3
	v_mov_b32_dpp v108, v160 row_ror:8 row_mask:0xf bank_mask:0xc
	v_mov_b32_dpp v109, v161 row_ror:8 row_mask:0xf bank_mask:0xc
	v_mov_b32_dpp v110, v162 row_ror:8 row_mask:0xf bank_mask:0xc
	v_mov_b32_dpp v111, v163 row_ror:8 row_mask:0xf bank_mask:0xc
	v_mov_b32_dpp v100, v164 row_ror:8 row_mask:0xf bank_mask:0xc
	v_mov_b32_dpp v101, v165 row_ror:8 row_mask:0xf bank_mask:0xc
	v_mov_b32_dpp v102, v166 row_ror:8 row_mask:0xf bank_mask:0xc
	v_mov_b32_dpp v103, v167 row_ror:8 row_mask:0xf bank_mask:0xc
	v_add_u32_e32 v147, 0x20000, v146
	v_add_u32_e32 v148, 0x30000, v146
	s_waitcnt vmcnt(12)
	v_pk_add_f32 v[108:109], v[108:109], v[184:185]
	v_pk_add_f32 v[110:111], v[110:111], v[186:187]
	v_pk_add_f32 v[104:105], v[104:105], v[188:189]
	v_pk_add_f32 v[106:107], v[106:107], v[190:191]
	v_pk_add_f32 v[100:101], v[100:101], v[192:193]
	v_pk_add_f32 v[102:103], v[102:103], v[194:195]
	v_pk_add_f32 v[96:97], v[96:97], v[196:197]
	v_pk_add_f32 v[98:99], v[98:99], v[198:199]
	global_store_dwordx4 v147, v[108:111], s[78:79]
	global_store_dwordx4 v148, v[104:107], s[78:79]
	global_store_dwordx4 v147, v[100:103], s[78:79] offset:512
	global_store_dwordx4 v148, v[96:99], s[78:79] offset:512
	v_add_u32_e32 v147, 0x100000, v146
	v_add_u32_e32 v148, 0x110000, v146
	global_load_dwordx4 v[184:187], v147, s[76:77]
	global_load_dwordx4 v[188:191], v148, s[76:77]
	global_load_dwordx4 v[192:195], v147, s[76:77] offset:512
	global_load_dwordx4 v[196:199], v148, s[76:77] offset:512
	v_mov_b32_e32 v160, v88
	v_mov_b32_e32 v161, v89
	v_mov_b32_e32 v162, v90
	v_mov_b32_e32 v163, v91
	v_mov_b32_e32 v164, v80
	v_mov_b32_e32 v165, v81
	v_mov_b32_e32 v166, v82
	v_mov_b32_e32 v167, v83
	v_mov_b32_dpp v88, v92 row_ror:8 row_mask:0xf bank_mask:0x3
	v_mov_b32_dpp v89, v93 row_ror:8 row_mask:0xf bank_mask:0x3
	v_mov_b32_dpp v90, v94 row_ror:8 row_mask:0xf bank_mask:0x3
	v_mov_b32_dpp v91, v95 row_ror:8 row_mask:0xf bank_mask:0x3
	v_mov_b32_dpp v80, v84 row_ror:8 row_mask:0xf bank_mask:0x3
	v_mov_b32_dpp v81, v85 row_ror:8 row_mask:0xf bank_mask:0x3
	v_mov_b32_dpp v82, v86 row_ror:8 row_mask:0xf bank_mask:0x3
	v_mov_b32_dpp v83, v87 row_ror:8 row_mask:0xf bank_mask:0x3
	v_mov_b32_dpp v92, v160 row_ror:8 row_mask:0xf bank_mask:0xc
	v_mov_b32_dpp v93, v161 row_ror:8 row_mask:0xf bank_mask:0xc
	v_mov_b32_dpp v94, v162 row_ror:8 row_mask:0xf bank_mask:0xc
	v_mov_b32_dpp v95, v163 row_ror:8 row_mask:0xf bank_mask:0xc
	v_mov_b32_dpp v84, v164 row_ror:8 row_mask:0xf bank_mask:0xc
	v_mov_b32_dpp v85, v165 row_ror:8 row_mask:0xf bank_mask:0xc
	v_mov_b32_dpp v86, v166 row_ror:8 row_mask:0xf bank_mask:0xc
	v_mov_b32_dpp v87, v167 row_ror:8 row_mask:0xf bank_mask:0xc
	v_add_u32_e32 v147, 0x40000, v146
	v_add_u32_e32 v148, 0x50000, v146
	s_waitcnt vmcnt(16)
	v_pk_add_f32 v[92:93], v[92:93], v[200:201]
	v_pk_add_f32 v[94:95], v[94:95], v[202:203]
	v_pk_add_f32 v[88:89], v[88:89], v[204:205]
	v_pk_add_f32 v[90:91], v[90:91], v[206:207]
	v_pk_add_f32 v[84:85], v[84:85], v[208:209]
	v_pk_add_f32 v[86:87], v[86:87], v[210:211]
	v_pk_add_f32 v[80:81], v[80:81], v[212:213]
	v_pk_add_f32 v[82:83], v[82:83], v[214:215]
	global_store_dwordx4 v147, v[92:95], s[78:79]
	global_store_dwordx4 v148, v[88:91], s[78:79]
	global_store_dwordx4 v147, v[84:87], s[78:79] offset:512
	global_store_dwordx4 v148, v[80:83], s[78:79] offset:512
	v_add_u32_e32 v147, 0x120000, v146
	v_add_u32_e32 v148, 0x130000, v146
	global_load_dwordx4 v[200:203], v147, s[76:77]
	global_load_dwordx4 v[204:207], v148, s[76:77]
	global_load_dwordx4 v[208:211], v147, s[76:77] offset:512
	global_load_dwordx4 v[212:215], v148, s[76:77] offset:512
	v_mov_b32_e32 v160, v72
	v_mov_b32_e32 v161, v73
	v_mov_b32_e32 v162, v74
	v_mov_b32_e32 v163, v75
	v_mov_b32_e32 v164, v64
	v_mov_b32_e32 v165, v65
	v_mov_b32_e32 v166, v66
	v_mov_b32_e32 v167, v67
	v_mov_b32_dpp v72, v76 row_ror:8 row_mask:0xf bank_mask:0x3
	v_mov_b32_dpp v73, v77 row_ror:8 row_mask:0xf bank_mask:0x3
	v_mov_b32_dpp v74, v78 row_ror:8 row_mask:0xf bank_mask:0x3
	v_mov_b32_dpp v75, v79 row_ror:8 row_mask:0xf bank_mask:0x3
	v_mov_b32_dpp v64, v68 row_ror:8 row_mask:0xf bank_mask:0x3
	v_mov_b32_dpp v65, v69 row_ror:8 row_mask:0xf bank_mask:0x3
	v_mov_b32_dpp v66, v70 row_ror:8 row_mask:0xf bank_mask:0x3
	v_mov_b32_dpp v67, v71 row_ror:8 row_mask:0xf bank_mask:0x3
	v_mov_b32_dpp v76, v160 row_ror:8 row_mask:0xf bank_mask:0xc
	v_mov_b32_dpp v77, v161 row_ror:8 row_mask:0xf bank_mask:0xc
	v_mov_b32_dpp v78, v162 row_ror:8 row_mask:0xf bank_mask:0xc
	v_mov_b32_dpp v79, v163 row_ror:8 row_mask:0xf bank_mask:0xc
	v_mov_b32_dpp v68, v164 row_ror:8 row_mask:0xf bank_mask:0xc
	v_mov_b32_dpp v69, v165 row_ror:8 row_mask:0xf bank_mask:0xc
	v_mov_b32_dpp v70, v166 row_ror:8 row_mask:0xf bank_mask:0xc
	v_mov_b32_dpp v71, v167 row_ror:8 row_mask:0xf bank_mask:0xc
	v_add_u32_e32 v147, 0x60000, v146
	v_add_u32_e32 v148, 0x70000, v146
	s_waitcnt vmcnt(16)
	v_pk_add_f32 v[76:77], v[76:77], v[168:169]
	v_pk_add_f32 v[78:79], v[78:79], v[170:171]
	v_pk_add_f32 v[72:73], v[72:73], v[172:173]
	v_pk_add_f32 v[74:75], v[74:75], v[174:175]
	v_pk_add_f32 v[68:69], v[68:69], v[176:177]
	v_pk_add_f32 v[70:71], v[70:71], v[178:179]
	v_pk_add_f32 v[64:65], v[64:65], v[180:181]
	v_pk_add_f32 v[66:67], v[66:67], v[182:183]
	global_store_dwordx4 v147, v[76:79], s[78:79]
	global_store_dwordx4 v148, v[72:75], s[78:79]
	global_store_dwordx4 v147, v[68:71], s[78:79] offset:512
	global_store_dwordx4 v148, v[64:67], s[78:79] offset:512
	v_add_u32_e32 v147, 0x140000, v146
	v_add_u32_e32 v148, 0x150000, v146
	global_load_dwordx4 v[168:171], v147, s[76:77]
	global_load_dwordx4 v[172:175], v148, s[76:77]
	global_load_dwordx4 v[176:179], v147, s[76:77] offset:512
	global_load_dwordx4 v[180:183], v148, s[76:77] offset:512
	v_mov_b32_e32 v160, v56
	v_mov_b32_e32 v161, v57
	v_mov_b32_e32 v162, v58
	v_mov_b32_e32 v163, v59
	v_mov_b32_e32 v164, v48
	v_mov_b32_e32 v165, v49
	v_mov_b32_e32 v166, v50
	v_mov_b32_e32 v167, v51
	v_mov_b32_dpp v56, v60 row_ror:8 row_mask:0xf bank_mask:0x3
	v_mov_b32_dpp v57, v61 row_ror:8 row_mask:0xf bank_mask:0x3
	v_mov_b32_dpp v58, v62 row_ror:8 row_mask:0xf bank_mask:0x3
	v_mov_b32_dpp v59, v63 row_ror:8 row_mask:0xf bank_mask:0x3
	v_mov_b32_dpp v48, v52 row_ror:8 row_mask:0xf bank_mask:0x3
	v_mov_b32_dpp v49, v53 row_ror:8 row_mask:0xf bank_mask:0x3
	v_mov_b32_dpp v50, v54 row_ror:8 row_mask:0xf bank_mask:0x3
	v_mov_b32_dpp v51, v55 row_ror:8 row_mask:0xf bank_mask:0x3
	v_mov_b32_dpp v60, v160 row_ror:8 row_mask:0xf bank_mask:0xc
	v_mov_b32_dpp v61, v161 row_ror:8 row_mask:0xf bank_mask:0xc
	v_mov_b32_dpp v62, v162 row_ror:8 row_mask:0xf bank_mask:0xc
	v_mov_b32_dpp v63, v163 row_ror:8 row_mask:0xf bank_mask:0xc
	v_mov_b32_dpp v52, v164 row_ror:8 row_mask:0xf bank_mask:0xc
	v_mov_b32_dpp v53, v165 row_ror:8 row_mask:0xf bank_mask:0xc
	v_mov_b32_dpp v54, v166 row_ror:8 row_mask:0xf bank_mask:0xc
	v_mov_b32_dpp v55, v167 row_ror:8 row_mask:0xf bank_mask:0xc
	v_add_u32_e32 v147, 0x100000, v146
	v_add_u32_e32 v148, 0x110000, v146
	s_waitcnt vmcnt(16)
	v_pk_add_f32 v[60:61], v[60:61], v[184:185]
	v_pk_add_f32 v[62:63], v[62:63], v[186:187]
	v_pk_add_f32 v[56:57], v[56:57], v[188:189]
	v_pk_add_f32 v[58:59], v[58:59], v[190:191]
	v_pk_add_f32 v[52:53], v[52:53], v[192:193]
	v_pk_add_f32 v[54:55], v[54:55], v[194:195]
	v_pk_add_f32 v[48:49], v[48:49], v[196:197]
	v_pk_add_f32 v[50:51], v[50:51], v[198:199]
	global_store_dwordx4 v147, v[60:63], s[78:79]
	global_store_dwordx4 v148, v[56:59], s[78:79]
	global_store_dwordx4 v147, v[52:55], s[78:79] offset:512
	global_store_dwordx4 v148, v[48:51], s[78:79] offset:512
	v_add_u32_e32 v147, 0x160000, v146
	v_add_u32_e32 v148, 0x170000, v146
	global_load_dwordx4 v[184:187], v147, s[76:77]
	global_load_dwordx4 v[188:191], v148, s[76:77]
	global_load_dwordx4 v[192:195], v147, s[76:77] offset:512
	global_load_dwordx4 v[196:199], v148, s[76:77] offset:512
	v_mov_b32_e32 v160, v40
	v_mov_b32_e32 v161, v41
	v_mov_b32_e32 v162, v42
	v_mov_b32_e32 v163, v43
	v_mov_b32_e32 v164, v32
	v_mov_b32_e32 v165, v33
	v_mov_b32_e32 v166, v34
	v_mov_b32_e32 v167, v35
	v_mov_b32_dpp v40, v44 row_ror:8 row_mask:0xf bank_mask:0x3
	v_mov_b32_dpp v41, v45 row_ror:8 row_mask:0xf bank_mask:0x3
	v_mov_b32_dpp v42, v46 row_ror:8 row_mask:0xf bank_mask:0x3
	v_mov_b32_dpp v43, v47 row_ror:8 row_mask:0xf bank_mask:0x3
	v_mov_b32_dpp v32, v36 row_ror:8 row_mask:0xf bank_mask:0x3
	v_mov_b32_dpp v33, v37 row_ror:8 row_mask:0xf bank_mask:0x3
	v_mov_b32_dpp v34, v38 row_ror:8 row_mask:0xf bank_mask:0x3
	v_mov_b32_dpp v35, v39 row_ror:8 row_mask:0xf bank_mask:0x3
	v_mov_b32_dpp v44, v160 row_ror:8 row_mask:0xf bank_mask:0xc
	v_mov_b32_dpp v45, v161 row_ror:8 row_mask:0xf bank_mask:0xc
	v_mov_b32_dpp v46, v162 row_ror:8 row_mask:0xf bank_mask:0xc
	v_mov_b32_dpp v47, v163 row_ror:8 row_mask:0xf bank_mask:0xc
	v_mov_b32_dpp v36, v164 row_ror:8 row_mask:0xf bank_mask:0xc
	v_mov_b32_dpp v37, v165 row_ror:8 row_mask:0xf bank_mask:0xc
	v_mov_b32_dpp v38, v166 row_ror:8 row_mask:0xf bank_mask:0xc
	v_mov_b32_dpp v39, v167 row_ror:8 row_mask:0xf bank_mask:0xc
	v_add_u32_e32 v147, 0x120000, v146
	v_add_u32_e32 v148, 0x130000, v146
	s_waitcnt vmcnt(16)
	v_pk_add_f32 v[44:45], v[44:45], v[200:201]
	v_pk_add_f32 v[46:47], v[46:47], v[202:203]
	v_pk_add_f32 v[40:41], v[40:41], v[204:205]
	v_pk_add_f32 v[42:43], v[42:43], v[206:207]
	v_pk_add_f32 v[36:37], v[36:37], v[208:209]
	v_pk_add_f32 v[38:39], v[38:39], v[210:211]
	v_pk_add_f32 v[32:33], v[32:33], v[212:213]
	v_pk_add_f32 v[34:35], v[34:35], v[214:215]
	global_store_dwordx4 v147, v[44:47], s[78:79]
	global_store_dwordx4 v148, v[40:43], s[78:79]
	global_store_dwordx4 v147, v[36:39], s[78:79] offset:512
	global_store_dwordx4 v148, v[32:35], s[78:79] offset:512
	v_mov_b32_e32 v160, v24
	v_mov_b32_e32 v161, v25
	v_mov_b32_e32 v162, v26
	v_mov_b32_e32 v163, v27
	v_mov_b32_e32 v164, v16
	v_mov_b32_e32 v165, v17
	v_mov_b32_e32 v166, v18
	v_mov_b32_e32 v167, v19
	v_mov_b32_dpp v24, v28 row_ror:8 row_mask:0xf bank_mask:0x3
	v_mov_b32_dpp v25, v29 row_ror:8 row_mask:0xf bank_mask:0x3
	v_mov_b32_dpp v26, v30 row_ror:8 row_mask:0xf bank_mask:0x3
	v_mov_b32_dpp v27, v31 row_ror:8 row_mask:0xf bank_mask:0x3
	v_mov_b32_dpp v16, v20 row_ror:8 row_mask:0xf bank_mask:0x3
	v_mov_b32_dpp v17, v21 row_ror:8 row_mask:0xf bank_mask:0x3
	v_mov_b32_dpp v18, v22 row_ror:8 row_mask:0xf bank_mask:0x3
	v_mov_b32_dpp v19, v23 row_ror:8 row_mask:0xf bank_mask:0x3
	v_mov_b32_dpp v28, v160 row_ror:8 row_mask:0xf bank_mask:0xc
	v_mov_b32_dpp v29, v161 row_ror:8 row_mask:0xf bank_mask:0xc
	v_mov_b32_dpp v30, v162 row_ror:8 row_mask:0xf bank_mask:0xc
	v_mov_b32_dpp v31, v163 row_ror:8 row_mask:0xf bank_mask:0xc
	v_mov_b32_dpp v20, v164 row_ror:8 row_mask:0xf bank_mask:0xc
	v_mov_b32_dpp v21, v165 row_ror:8 row_mask:0xf bank_mask:0xc
	v_mov_b32_dpp v22, v166 row_ror:8 row_mask:0xf bank_mask:0xc
	v_mov_b32_dpp v23, v167 row_ror:8 row_mask:0xf bank_mask:0xc
	v_add_u32_e32 v147, 0x140000, v146
	v_add_u32_e32 v148, 0x150000, v146
	s_waitcnt vmcnt(12)
	v_pk_add_f32 v[28:29], v[28:29], v[168:169]
	v_pk_add_f32 v[30:31], v[30:31], v[170:171]
	v_pk_add_f32 v[24:25], v[24:25], v[172:173]
	v_pk_add_f32 v[26:27], v[26:27], v[174:175]
	v_pk_add_f32 v[20:21], v[20:21], v[176:177]
	v_pk_add_f32 v[22:23], v[22:23], v[178:179]
	v_pk_add_f32 v[16:17], v[16:17], v[180:181]
	v_pk_add_f32 v[18:19], v[18:19], v[182:183]
	global_store_dwordx4 v147, v[28:31], s[78:79]
	global_store_dwordx4 v148, v[24:27], s[78:79]
	global_store_dwordx4 v147, v[20:23], s[78:79] offset:512
	global_store_dwordx4 v148, v[16:19], s[78:79] offset:512
	v_mov_b32_e32 v160, v8
	v_mov_b32_e32 v161, v9
	v_mov_b32_e32 v162, v10
	v_mov_b32_e32 v163, v11
	v_mov_b32_e32 v164, v0
	v_mov_b32_e32 v165, v1
	v_mov_b32_e32 v166, v2
	v_mov_b32_e32 v167, v3
	v_mov_b32_dpp v8, v12 row_ror:8 row_mask:0xf bank_mask:0x3
	v_mov_b32_dpp v9, v13 row_ror:8 row_mask:0xf bank_mask:0x3
	v_mov_b32_dpp v10, v14 row_ror:8 row_mask:0xf bank_mask:0x3
	v_mov_b32_dpp v11, v15 row_ror:8 row_mask:0xf bank_mask:0x3
	v_mov_b32_dpp v0, v4 row_ror:8 row_mask:0xf bank_mask:0x3
	v_mov_b32_dpp v1, v5 row_ror:8 row_mask:0xf bank_mask:0x3
	v_mov_b32_dpp v2, v6 row_ror:8 row_mask:0xf bank_mask:0x3
	v_mov_b32_dpp v3, v7 row_ror:8 row_mask:0xf bank_mask:0x3
	v_mov_b32_dpp v12, v160 row_ror:8 row_mask:0xf bank_mask:0xc
	v_mov_b32_dpp v13, v161 row_ror:8 row_mask:0xf bank_mask:0xc
	v_mov_b32_dpp v14, v162 row_ror:8 row_mask:0xf bank_mask:0xc
	v_mov_b32_dpp v15, v163 row_ror:8 row_mask:0xf bank_mask:0xc
	v_mov_b32_dpp v4, v164 row_ror:8 row_mask:0xf bank_mask:0xc
	v_mov_b32_dpp v5, v165 row_ror:8 row_mask:0xf bank_mask:0xc
	v_mov_b32_dpp v6, v166 row_ror:8 row_mask:0xf bank_mask:0xc
	v_mov_b32_dpp v7, v167 row_ror:8 row_mask:0xf bank_mask:0xc
	v_add_u32_e32 v147, 0x160000, v146
	v_add_u32_e32 v148, 0x170000, v146
	s_waitcnt vmcnt(8)
	v_pk_add_f32 v[12:13], v[12:13], v[184:185]
	v_pk_add_f32 v[14:15], v[14:15], v[186:187]
	v_pk_add_f32 v[8:9], v[8:9], v[188:189]
	v_pk_add_f32 v[10:11], v[10:11], v[190:191]
	v_pk_add_f32 v[4:5], v[4:5], v[192:193]
	v_pk_add_f32 v[6:7], v[6:7], v[194:195]
	v_pk_add_f32 v[0:1], v[0:1], v[196:197]
	v_pk_add_f32 v[2:3], v[2:3], v[198:199]
	global_store_dwordx4 v147, v[12:15], s[78:79]
	global_store_dwordx4 v148, v[8:11], s[78:79]
	global_store_dwordx4 v147, v[4:7], s[78:79] offset:512
	global_store_dwordx4 v148, v[0:3], s[78:79] offset:512
	s_branch .LBB0_1625
